# priority raised before each half-step's first LDS reads (s_setprio 1 moved ahead of the up-front ds_reads) in all fast K-loops; fast tail iteration at mixed/x1/peerq
# speedup vs baseline: 1.0288x; 1.0034x over previous
; DI void gemm_ldg(const bf16_t* ga, const bf16_t* gb, int lda, int ldb, int koff, u32x4 (&ra)[4], u32x4 (&rb)[4]) {
; #pragma unroll
;   for (int i = 0; i < 4; ++i) {
;     ra[i] = *(const u32x4*)(ga + (size_t)(32 * i) * lda + koff);
;     rb[i] = *(const u32x4*)(gb + (size_t)(32 * i) * ldb + koff);
;   }
; }
; DI void gemm_sts(bf16_t* dA, bf16_t* dB, int r0, int c0, const u32x4 (&ra)[4], const u32x4 (&rb)[4]) {
; #pragma unroll
;   for (int i = 0; i < 4; ++i) {
;     *(u32x4*)(dA + (r0 + 32 * i) * LDT + c0 * 8) = ra[i];
;     *(u32x4*)(dB + (r0 + 32 * i) * LDT + c0 * 8) = rb[i];
;   }
; }
; DI void gemm_mma(const bf16_t* a_, const bf16_t* b_, f32x16 (&acc)[2][2]) {
;   __builtin_amdgcn_s_setprio(1);
; #pragma unroll
;   for (int kk = 0; kk < 4; ++kk) {
;     bf16x8 a0 = *(const bf16x8*)(a_ + kk * 16);
;     bf16x8 a1 = *(const bf16x8*)(a_ + 32 * LDT + kk * 16);
;     bf16x8 b0 = *(const bf16x8*)(b_ + kk * 16);
;     bf16x8 b1 = *(const bf16x8*)(b_ + 32 * LDT + kk * 16);
;     acc[0][0] = MFMA(a0, b0, acc[0][0]);
;     acc[0][1] = MFMA(a0, b1, acc[0][1]);
;     acc[1][0] = MFMA(a1, b0, acc[1][0]);
;     acc[1][1] = MFMA(a1, b1, acc[1][1]);
;   }
;   __builtin_amdgcn_s_setprio(0);
; }
; DI void gemm_tile(const bf16_t* __restrict__ A, int lda, const bf16_t* __restrict__ B, int ldb, int K,
;                   f32x16 (&acc)[2][2], char* smem) {
;   const int tid = threadIdx.x, lane = tid & 63, w = tid >> 6, wm = w >> 1, wn = w & 1;
;   bf16_t* sA = (bf16_t*)smem;
;   bf16_t* sB = sA + 2 * 128 * LDT;
;   const int r0 = tid >> 3, c0 = tid & 7;
;   const bf16_t* ga = A + (size_t)r0 * lda + c0 * 8;
;   const bf16_t* gb = B + (size_t)r0 * ldb + c0 * 8;
;   const int aoff = (wm * 64 + (lane & 31)) * LDT + (lane >> 5) * 8;
;   const int boff = (wn * 64 + (lane & 31)) * LDT + (lane >> 5) * 8;
;   u32x4 ra0[4], rb0[4], ra1[4], rb1[4];
;   gemm_ldg(ga, gb, lda, ldb, 0, ra0, rb0);
;   gemm_ldg(ga, gb, lda, ldb, 64, ra1, rb1);
;   __syncthreads();
;   gemm_sts(sA, sB, r0, c0, ra0, rb0);
;   __syncthreads();
;   const int nk = K >> 6;
; #pragma unroll 1
;   for (int kt = 0; kt < nk; kt += 2) {
;     if (kt + 2 < nk) gemm_ldg(ga, gb, lda, ldb, (kt + 2) * 64, ra0, rb0);
;     gemm_mma(sA + aoff, sB + boff, acc);
;     gemm_sts(sA + 128 * LDT, sB + 128 * LDT, r0, c0, ra1, rb1);
;     __syncthreads();
;     if (kt + 3 < nk) gemm_ldg(ga, gb, lda, ldb, (kt + 3) * 64, ra1, rb1);
.Lfast1_top:
	s_setprio 1
	ds_read_b128 v[166:169], v156
	ds_read_b128 v[170:173], v157 offset:36864
	ds_read_b128 v[174:177], v157 offset:41472
	ds_read_b128 v[178:181], v156 offset:4608
	ds_read_b128 v[182:185], v156 offset:32
	ds_read_b128 v[186:189], v157 offset:36896
	ds_read_b128 v[190:193], v157 offset:41504
	ds_read_b128 v[194:197], v156 offset:4640
	s_waitcnt lgkmcnt(6)
	v_mfma_f32_32x32x16_bf16 v[50:65], v[166:169], v[170:173], v[50:65]
	ds_read_b128 v[198:201], v156 offset:64
	global_load_dwordx4 v[66:69], v216, s[84:85] offset:256
	s_waitcnt lgkmcnt(6)
	v_mfma_f32_32x32x16_bf16 v[34:49], v[166:169], v[174:177], v[34:49]
	ds_read_b128 v[202:205], v157 offset:36928
	global_load_dwordx4 v[70:73], v217, s[84:85] offset:256
	s_waitcnt lgkmcnt(6)
	v_mfma_f32_32x32x16_bf16 v[18:33], v[178:181], v[170:173], v[18:33]
	ds_read_b128 v[206:209], v157 offset:41536
	global_load_dwordx4 v[74:77], v217, s[86:87] offset:256
	v_mfma_f32_32x32x16_bf16 v[2:17], v[178:181], v[174:177], v[2:17]
	ds_read_b128 v[210:213], v156 offset:4672
	global_load_dwordx4 v[78:81], v218, s[84:85] offset:256
	s_waitcnt lgkmcnt(6)
	v_mfma_f32_32x32x16_bf16 v[50:65], v[182:185], v[186:189], v[50:65]
	ds_read_b128 v[166:169], v156 offset:96
	global_load_dwordx4 v[82:85], v218, s[86:87] offset:256
	s_waitcnt lgkmcnt(6)
	v_mfma_f32_32x32x16_bf16 v[34:49], v[182:185], v[190:193], v[34:49]
	ds_read_b128 v[170:173], v157 offset:36960
	global_load_dwordx4 v[86:89], v219, s[84:85] offset:256
	s_waitcnt lgkmcnt(6)
	v_mfma_f32_32x32x16_bf16 v[18:33], v[194:197], v[186:189], v[18:33]
	ds_read_b128 v[174:177], v157 offset:41568
	global_load_dwordx4 v[90:93], v216, s[86:87] offset:256
	v_mfma_f32_32x32x16_bf16 v[2:17], v[194:197], v[190:193], v[2:17]
	ds_read_b128 v[178:181], v156 offset:4704
	global_load_dwordx4 v[102:105], v219, s[86:87] offset:256
	s_waitcnt lgkmcnt(6)
	v_mfma_f32_32x32x16_bf16 v[50:65], v[198:201], v[202:205], v[50:65]
	s_waitcnt vmcnt(8)
	ds_write_b128 v1, v[94:97] offset:18432
	s_waitcnt lgkmcnt(6)
	v_mfma_f32_32x32x16_bf16 v[34:49], v[198:201], v[206:209], v[34:49]
	ds_write_b128 v1, v[122:125] offset:55296
	s_waitcnt lgkmcnt(6)
	v_mfma_f32_32x32x16_bf16 v[18:33], v[210:213], v[202:205], v[18:33]
	ds_write_b128 v1, v[98:101] offset:23040
	v_mfma_f32_32x32x16_bf16 v[2:17], v[210:213], v[206:209], v[2:17]
	ds_write_b128 v1, v[106:109] offset:59904
	s_waitcnt lgkmcnt(6)
	v_mfma_f32_32x32x16_bf16 v[50:65], v[166:169], v[170:173], v[50:65]
	ds_write_b128 v1, v[110:113] offset:27648
	s_waitcnt lgkmcnt(6)
	v_mfma_f32_32x32x16_bf16 v[34:49], v[166:169], v[174:177], v[34:49]
	ds_write_b128 v1, v[114:117] offset:64512
	s_waitcnt lgkmcnt(6)
	v_mfma_f32_32x32x16_bf16 v[18:33], v[178:181], v[170:173], v[18:33]
	ds_write_b128 v1, v[118:121] offset:32256
	v_mfma_f32_32x32x16_bf16 v[2:17], v[178:181], v[174:177], v[2:17]
	ds_write_b128 v158, v[126:129] offset:13824
	s_setprio 0
	s_waitcnt lgkmcnt(0)
	s_barrier
	s_setprio 1
	ds_read_b128 v[166:169], v156 offset:18432
	ds_read_b128 v[170:173], v157 offset:55296
	ds_read_b128 v[174:177], v157 offset:59904
	ds_read_b128 v[178:181], v156 offset:23040
	ds_read_b128 v[182:185], v156 offset:18464
	ds_read_b128 v[186:189], v157 offset:55328
	ds_read_b128 v[190:193], v157 offset:59936
	ds_read_b128 v[194:197], v156 offset:23072
	s_waitcnt lgkmcnt(6)
	v_mfma_f32_32x32x16_bf16 v[50:65], v[166:169], v[170:173], v[50:65]
	ds_read_b128 v[198:201], v156 offset:18496
	global_load_dwordx4 v[94:97], v216, s[84:85] offset:384
	s_waitcnt lgkmcnt(6)
	v_mfma_f32_32x32x16_bf16 v[34:49], v[166:169], v[174:177], v[34:49]
	ds_read_b128 v[202:205], v157 offset:55360
	global_load_dwordx4 v[98:101], v217, s[84:85] offset:384
	s_waitcnt lgkmcnt(6)
	v_mfma_f32_32x32x16_bf16 v[18:33], v[178:181], v[170:173], v[18:33]
	ds_read_b128 v[206:209], v157 offset:59968
	global_load_dwordx4 v[106:109], v217, s[86:87] offset:384
	v_mfma_f32_32x32x16_bf16 v[2:17], v[178:181], v[174:177], v[2:17]
	ds_read_b128 v[210:213], v156 offset:23104
	global_load_dwordx4 v[110:113], v218, s[84:85] offset:384
	s_waitcnt lgkmcnt(6)
	v_mfma_f32_32x32x16_bf16 v[50:65], v[182:185], v[186:189], v[50:65]
	ds_read_b128 v[166:169], v156 offset:18528
	global_load_dwordx4 v[114:117], v218, s[86:87] offset:384
	s_waitcnt lgkmcnt(6)
	v_mfma_f32_32x32x16_bf16 v[34:49], v[182:185], v[190:193], v[34:49]
	ds_read_b128 v[170:173], v157 offset:55392
	global_load_dwordx4 v[118:121], v219, s[84:85] offset:384
	s_waitcnt lgkmcnt(6)
	v_mfma_f32_32x32x16_bf16 v[18:33], v[194:197], v[186:189], v[18:33]
	ds_read_b128 v[174:177], v157 offset:60000
	global_load_dwordx4 v[122:125], v216, s[86:87] offset:384
	v_mfma_f32_32x32x16_bf16 v[2:17], v[194:197], v[190:193], v[2:17]
	ds_read_b128 v[178:181], v156 offset:23136
	global_load_dwordx4 v[126:129], v219, s[86:87] offset:384
	s_waitcnt lgkmcnt(6)
	v_mfma_f32_32x32x16_bf16 v[50:65], v[198:201], v[202:205], v[50:65]
	s_waitcnt vmcnt(8)
	ds_write_b128 v1, v[66:69]
	s_waitcnt lgkmcnt(6)
	v_mfma_f32_32x32x16_bf16 v[34:49], v[198:201], v[206:209], v[34:49]
	ds_write_b128 v1, v[90:93] offset:36864
	s_waitcnt lgkmcnt(6)
	v_mfma_f32_32x32x16_bf16 v[18:33], v[210:213], v[202:205], v[18:33]
	ds_write_b128 v1, v[70:73] offset:4608
	v_mfma_f32_32x32x16_bf16 v[2:17], v[210:213], v[206:209], v[2:17]
	ds_write_b128 v1, v[74:77] offset:41472
	s_waitcnt lgkmcnt(6)
	v_mfma_f32_32x32x16_bf16 v[50:65], v[166:169], v[170:173], v[50:65]
	ds_write_b128 v1, v[78:81] offset:9216
	s_waitcnt lgkmcnt(6)
	v_mfma_f32_32x32x16_bf16 v[34:49], v[166:169], v[174:177], v[34:49]
	ds_write_b128 v1, v[82:85] offset:46080
	s_waitcnt lgkmcnt(6)
	v_mfma_f32_32x32x16_bf16 v[18:33], v[178:181], v[170:173], v[18:33]
	ds_write_b128 v1, v[86:89] offset:13824
	v_mfma_f32_32x32x16_bf16 v[2:17], v[178:181], v[174:177], v[2:17]
	ds_write_b128 v1, v[102:105] offset:50688
	s_setprio 0
	s_add_i32 s8, s8, 2
	s_add_u32 s84, s84, 0x100
	s_addc_u32 s85, s85, 0
	s_add_u32 s86, s86, 0x100
	s_addc_u32 s87, s87, 0
	s_waitcnt lgkmcnt(0)
	s_barrier
	s_cmp_lt_u32 s8, 14
	s_cbranch_scc1 .Lfast1_top
	s_branch .LBB0_102

; DI void gemm_ldg(const bf16_t* ga, const bf16_t* gb, int lda, int ldb, int koff, u32x4 (&ra)[4], u32x4 (&rb)[4]) {
; #pragma unroll
;   for (int i = 0; i < 4; ++i) {
;     ra[i] = *(const u32x4*)(ga + (size_t)(32 * i) * lda + koff);
;     rb[i] = *(const u32x4*)(gb + (size_t)(32 * i) * ldb + koff);
;   }
; }
; DI void gemm_sts(bf16_t* dA, bf16_t* dB, int r0, int c0, const u32x4 (&ra)[4], const u32x4 (&rb)[4]) {
; #pragma unroll
;   for (int i = 0; i < 4; ++i) {
;     *(u32x4*)(dA + (r0 + 32 * i) * LDT + c0 * 8) = ra[i];
;     *(u32x4*)(dB + (r0 + 32 * i) * LDT + c0 * 8) = rb[i];
;   }
; }
; DI void gemm_mma(const bf16_t* a_, const bf16_t* b_, f32x16 (&acc)[2][2]) {
;   __builtin_amdgcn_s_setprio(1);
; #pragma unroll
;   for (int kk = 0; kk < 4; ++kk) {
;     bf16x8 a0 = *(const bf16x8*)(a_ + kk * 16);
;     bf16x8 a1 = *(const bf16x8*)(a_ + 32 * LDT + kk * 16);
;     bf16x8 b0 = *(const bf16x8*)(b_ + kk * 16);
;     bf16x8 b1 = *(const bf16x8*)(b_ + 32 * LDT + kk * 16);
;     acc[0][0] = MFMA(a0, b0, acc[0][0]);
;     acc[0][1] = MFMA(a0, b1, acc[0][1]);
;     acc[1][0] = MFMA(a1, b0, acc[1][0]);
;     acc[1][1] = MFMA(a1, b1, acc[1][1]);
;   }
;   __builtin_amdgcn_s_setprio(0);
; }
; DI void gemm_tile(const bf16_t* __restrict__ A, int lda, const bf16_t* __restrict__ B, int ldb, int K,
;                   f32x16 (&acc)[2][2], char* smem) {
;   const int tid = threadIdx.x, lane = tid & 63, w = tid >> 6, wm = w >> 1, wn = w & 1;
;   bf16_t* sA = (bf16_t*)smem;
;   bf16_t* sB = sA + 2 * 128 * LDT;
;   const int r0 = tid >> 3, c0 = tid & 7;
;   const bf16_t* ga = A + (size_t)r0 * lda + c0 * 8;
;   const bf16_t* gb = B + (size_t)r0 * ldb + c0 * 8;
;   const int aoff = (wm * 64 + (lane & 31)) * LDT + (lane >> 5) * 8;
;   const int boff = (wn * 64 + (lane & 31)) * LDT + (lane >> 5) * 8;
;   u32x4 ra0[4], rb0[4], ra1[4], rb1[4];
;   gemm_ldg(ga, gb, lda, ldb, 0, ra0, rb0);
;   gemm_ldg(ga, gb, lda, ldb, 64, ra1, rb1);
;   __syncthreads();
;   gemm_sts(sA, sB, r0, c0, ra0, rb0);
;   __syncthreads();
;   const int nk = K >> 6;
; #pragma unroll 1
;   for (int kt = 0; kt < nk; kt += 2) {
;     if (kt + 2 < nk) gemm_ldg(ga, gb, lda, ldb, (kt + 2) * 64, ra0, rb0);
;     gemm_mma(sA + aoff, sB + boff, acc);
;     gemm_sts(sA + 128 * LDT, sB + 128 * LDT, r0, c0, ra1, rb1);
;     __syncthreads();
;     if (kt + 3 < nk) gemm_ldg(ga, gb, lda, ldb, (kt + 3) * 64, ra1, rb1);
.Lgf2_top:
	s_add_i32 s44, s44, 2
	s_cmp_lt_u32 s44, 14
	s_cselect_b64 s[42:43], -1, 0
	s_cmp_gt_u32 s44, 13
	s_cselect_b64 s[40:41], -1, 0
	s_and_b64 vcc, exec, s[40:41]
	v_lshl_add_u64 v[222:223], s[34:35], 0, v[160:161]
	v_lshl_add_u64 v[220:221], v[218:219], 0, v[158:159]
	s_setprio 1
	ds_read_b128 v[240:243], v231
	ds_read_b128 v[244:247], v232 offset:36864
	ds_read_b128 v[248:251], v232 offset:41472
	ds_read_b128 v[252:255], v231 offset:4608
	s_waitcnt lgkmcnt(2)
	v_mfma_f32_32x32x16_bf16 v[50:65], v[240:243], v[244:247], v[50:65]
	v_add_co_u32_e32 v66, vcc, 0x5300000, v222
	s_nop 1
	v_addc_co_u32_e32 v67, vcc, 0, v223, vcc
	v_add_co_u32_e32 v70, vcc, 0x680000, v220
	global_load_dwordx4 v[66:69], v[66:67], off offset:256
	s_waitcnt lgkmcnt(1)
	v_mfma_f32_32x32x16_bf16 v[34:49], v[240:243], v[248:251], v[34:49]
	ds_read_b128 v[240:243], v231 offset:32
	s_nop 0
	v_addc_co_u32_e32 v71, vcc, 0, v221, vcc
	v_add_co_u32_e32 v74, vcc, 0x5310000, v222
	global_load_dwordx4 v[70:73], v[70:71], off offset:256
	s_waitcnt lgkmcnt(1)
	v_mfma_f32_32x32x16_bf16 v[18:33], v[252:255], v[244:247], v[18:33]
	ds_read_b128 v[244:247], v232 offset:36896
	s_nop 0
	v_addc_co_u32_e32 v75, vcc, 0, v223, vcc
	v_add_co_u32_e32 v82, vcc, 0x690000, v220
	global_load_dwordx4 v[74:77], v[74:75], off offset:256
	s_waitcnt lgkmcnt(2)
	v_mfma_f32_32x32x16_bf16 v[2:17], v[252:255], v[248:251], v[2:17]
	ds_read_b128 v[248:251], v232 offset:41504
	ds_read_b128 v[252:255], v231 offset:4640
	s_nop 0
	v_addc_co_u32_e32 v83, vcc, 0, v221, vcc
	v_add_co_u32_e32 v86, vcc, 0x5320000, v222
	global_load_dwordx4 v[82:85], v[82:83], off offset:256
	s_waitcnt lgkmcnt(2)
	v_mfma_f32_32x32x16_bf16 v[50:65], v[240:243], v[244:247], v[50:65]
	s_nop 0
	v_addc_co_u32_e32 v87, vcc, 0, v223, vcc
	v_add_co_u32_e32 v94, vcc, 0x6a0000, v220
	global_load_dwordx4 v[86:89], v[86:87], off offset:256
	s_waitcnt lgkmcnt(1)
	v_mfma_f32_32x32x16_bf16 v[34:49], v[240:243], v[248:251], v[34:49]
	ds_read_b128 v[240:243], v231 offset:64
	s_nop 0
	v_addc_co_u32_e32 v95, vcc, 0, v221, vcc
	v_add_co_u32_e32 v102, vcc, 0x5330000, v222
	global_load_dwordx4 v[94:97], v[94:95], off offset:256
	s_waitcnt lgkmcnt(1)
	v_mfma_f32_32x32x16_bf16 v[18:33], v[252:255], v[244:247], v[18:33]
	ds_read_b128 v[244:247], v232 offset:36928
	s_nop 0
	v_addc_co_u32_e32 v103, vcc, 0, v223, vcc
	v_add_co_u32_e32 v110, vcc, s64, v220
	global_load_dwordx4 v[102:105], v[102:103], off offset:256
	s_waitcnt lgkmcnt(2)
	v_mfma_f32_32x32x16_bf16 v[2:17], v[252:255], v[248:251], v[2:17]
	ds_read_b128 v[248:251], v232 offset:41536
	ds_read_b128 v[252:255], v231 offset:4672
	s_nop 0
	v_addc_co_u32_e32 v111, vcc, 0, v221, vcc
	global_load_dwordx4 v[110:113], v[110:111], off offset:256
	s_waitcnt lgkmcnt(2)
	v_mfma_f32_32x32x16_bf16 v[50:65], v[240:243], v[244:247], v[50:65]
	s_waitcnt vmcnt(8)
	ds_write_b128 v230, v[78:81] offset:18432
	s_waitcnt lgkmcnt(2)
	v_mfma_f32_32x32x16_bf16 v[34:49], v[240:243], v[248:251], v[34:49]
	ds_read_b128 v[240:243], v231 offset:96
	ds_write_b128 v230, v[114:117] offset:55296
	s_waitcnt lgkmcnt(3)
	v_mfma_f32_32x32x16_bf16 v[18:33], v[252:255], v[244:247], v[18:33]
	ds_read_b128 v[244:247], v232 offset:36960
	ds_write_b128 v230, v[90:93] offset:23040
	s_waitcnt lgkmcnt(5)
	v_mfma_f32_32x32x16_bf16 v[2:17], v[252:255], v[248:251], v[2:17]
	ds_read_b128 v[248:251], v232 offset:41568
	ds_read_b128 v[252:255], v231 offset:4704
	ds_write_b128 v230, v[118:121] offset:59904
	s_waitcnt lgkmcnt(4)
	v_mfma_f32_32x32x16_bf16 v[50:65], v[240:243], v[244:247], v[50:65]
	ds_write_b128 v230, v[98:101] offset:27648
	s_waitcnt lgkmcnt(3)
	v_mfma_f32_32x32x16_bf16 v[34:49], v[240:243], v[248:251], v[34:49]
	ds_write_b128 v230, v[122:125] offset:64512
	s_waitcnt lgkmcnt(3)
	v_mfma_f32_32x32x16_bf16 v[18:33], v[252:255], v[244:247], v[18:33]
	ds_write_b128 v230, v[106:109] offset:32256
	s_waitcnt lgkmcnt(4)
	v_mfma_f32_32x32x16_bf16 v[2:17], v[252:255], v[248:251], v[2:17]
	ds_write_b128 v233, v[126:129] offset:13824
	s_setprio 0
	s_waitcnt lgkmcnt(0)
	s_barrier
	s_setprio 1
	ds_read_b128 v[240:243], v231 offset:18432
	ds_read_b128 v[244:247], v232 offset:55296
	ds_read_b128 v[248:251], v232 offset:59904
	ds_read_b128 v[252:255], v231 offset:23040
	s_waitcnt lgkmcnt(2)
	v_mfma_f32_32x32x16_bf16 v[50:65], v[240:243], v[244:247], v[50:65]
	v_add_co_u32_e32 v78, vcc, 0x5300000, v222
	s_nop 1
	v_addc_co_u32_e32 v79, vcc, 0, v223, vcc
	v_add_co_u32_e32 v90, vcc, 0x680000, v220
	global_load_dwordx4 v[78:81], v[78:79], off offset:384
	s_waitcnt lgkmcnt(1)
	v_mfma_f32_32x32x16_bf16 v[34:49], v[240:243], v[248:251], v[34:49]
	ds_read_b128 v[240:243], v231 offset:18464
	s_nop 0
	v_addc_co_u32_e32 v91, vcc, 0, v221, vcc
	global_load_dwordx4 v[114:117], v[90:91], off offset:384
	s_waitcnt lgkmcnt(1)
	v_mfma_f32_32x32x16_bf16 v[18:33], v[252:255], v[244:247], v[18:33]
	ds_read_b128 v[244:247], v232 offset:55328
	v_add_co_u32_e32 v90, vcc, 0x5310000, v222
	s_nop 1
	v_addc_co_u32_e32 v91, vcc, 0, v223, vcc
	v_add_co_u32_e32 v98, vcc, 0x690000, v220
	global_load_dwordx4 v[90:93], v[90:91], off offset:384
	s_waitcnt lgkmcnt(2)
	v_mfma_f32_32x32x16_bf16 v[2:17], v[252:255], v[248:251], v[2:17]
	ds_read_b128 v[248:251], v232 offset:59936
	ds_read_b128 v[252:255], v231 offset:23072
	s_nop 0
	v_addc_co_u32_e32 v99, vcc, 0, v221, vcc
	global_load_dwordx4 v[118:121], v[98:99], off offset:384
	s_waitcnt lgkmcnt(2)
	v_mfma_f32_32x32x16_bf16 v[50:65], v[240:243], v[244:247], v[50:65]
	v_add_co_u32_e32 v98, vcc, 0x5320000, v222
	s_nop 1
	v_addc_co_u32_e32 v99, vcc, 0, v223, vcc
	v_add_co_u32_e32 v106, vcc, 0x6a0000, v220
	global_load_dwordx4 v[98:101], v[98:99], off offset:384
	s_waitcnt lgkmcnt(1)
; DI void gemm_ldg(const bf16_t* ga, const bf16_t* gb, int lda, int ldb, int koff, u32x4 (&ra)[4], u32x4 (&rb)[4]) {
; #pragma unroll
;   for (int i = 0; i < 4; ++i) {
;     ra[i] = *(const u32x4*)(ga + (size_t)(32 * i) * lda + koff);
;     rb[i] = *(const u32x4*)(gb + (size_t)(32 * i) * ldb + koff);
;   }
; }
; DI void gemm_sts(bf16_t* dA, bf16_t* dB, int r0, int c0, const u32x4 (&ra)[4], const u32x4 (&rb)[4]) {
; #pragma unroll
;   for (int i = 0; i < 4; ++i) {
;     *(u32x4*)(dA + (r0 + 32 * i) * LDT + c0 * 8) = ra[i];
;     *(u32x4*)(dB + (r0 + 32 * i) * LDT + c0 * 8) = rb[i];
;   }
; }
; DI void gemm_mma(const bf16_t* a_, const bf16_t* b_, f32x16 (&acc)[2][2]) {
;   __builtin_amdgcn_s_setprio(1);
; #pragma unroll
;   for (int kk = 0; kk < 4; ++kk) {
;     bf16x8 a0 = *(const bf16x8*)(a_ + kk * 16);
;     bf16x8 a1 = *(const bf16x8*)(a_ + 32 * LDT + kk * 16);
;     bf16x8 b0 = *(const bf16x8*)(b_ + kk * 16);
;     bf16x8 b1 = *(const bf16x8*)(b_ + 32 * LDT + kk * 16);
;     acc[0][0] = MFMA(a0, b0, acc[0][0]);
;     acc[0][1] = MFMA(a0, b1, acc[0][1]);
;     acc[1][0] = MFMA(a1, b0, acc[1][0]);
;     acc[1][1] = MFMA(a1, b1, acc[1][1]);
;   }
;   __builtin_amdgcn_s_setprio(0);
; }
; DI void gemm_tile(const bf16_t* __restrict__ A, int lda, const bf16_t* __restrict__ B, int ldb, int K,
;                   f32x16 (&acc)[2][2], char* smem) {
;   const int tid = threadIdx.x, lane = tid & 63, w = tid >> 6, wm = w >> 1, wn = w & 1;
;   bf16_t* sA = (bf16_t*)smem;
;   bf16_t* sB = sA + 2 * 128 * LDT;
;   const int r0 = tid >> 3, c0 = tid & 7;
;   const bf16_t* ga = A + (size_t)r0 * lda + c0 * 8;
;   const bf16_t* gb = B + (size_t)r0 * ldb + c0 * 8;
;   const int aoff = (wm * 64 + (lane & 31)) * LDT + (lane >> 5) * 8;
;   const int boff = (wn * 64 + (lane & 31)) * LDT + (lane >> 5) * 8;
;   u32x4 ra0[4], rb0[4], ra1[4], rb1[4];
;   gemm_ldg(ga, gb, lda, ldb, 0, ra0, rb0);
;   gemm_ldg(ga, gb, lda, ldb, 64, ra1, rb1);
;   __syncthreads();
;   gemm_sts(sA, sB, r0, c0, ra0, rb0);
;   __syncthreads();
;   const int nk = K >> 6;
; #pragma unroll 1
;   for (int kt = 0; kt < nk; kt += 2) {
;     if (kt + 2 < nk) gemm_ldg(ga, gb, lda, ldb, (kt + 2) * 64, ra0, rb0);
;     gemm_mma(sA + aoff, sB + boff, acc);
;     gemm_sts(sA + 128 * LDT, sB + 128 * LDT, r0, c0, ra1, rb1);
;     __syncthreads();
;     if (kt + 3 < nk) gemm_ldg(ga, gb, lda, ldb, (kt + 3) * 64, ra1, rb1);
	v_mfma_f32_32x32x16_bf16 v[34:49], v[240:243], v[248:251], v[34:49]
	ds_read_b128 v[240:243], v231 offset:18496
	s_nop 0
	v_addc_co_u32_e32 v107, vcc, 0, v221, vcc
	global_load_dwordx4 v[122:125], v[106:107], off offset:384
	s_waitcnt lgkmcnt(1)
	v_mfma_f32_32x32x16_bf16 v[18:33], v[252:255], v[244:247], v[18:33]
	ds_read_b128 v[244:247], v232 offset:55360
	v_add_co_u32_e32 v106, vcc, 0x5330000, v222
	s_nop 1
	v_addc_co_u32_e32 v107, vcc, 0, v223, vcc
	v_add_co_u32_e32 v126, vcc, 0x6b0000, v220
	global_load_dwordx4 v[106:109], v[106:107], off offset:384
	s_waitcnt lgkmcnt(2)
	v_mfma_f32_32x32x16_bf16 v[2:17], v[252:255], v[248:251], v[2:17]
	ds_read_b128 v[248:251], v232 offset:59968
	ds_read_b128 v[252:255], v231 offset:23104
	s_nop 0
	v_addc_co_u32_e32 v127, vcc, 0, v221, vcc
	global_load_dwordx4 v[126:129], v[126:127], off offset:384
	s_waitcnt lgkmcnt(2)
	v_mfma_f32_32x32x16_bf16 v[50:65], v[240:243], v[244:247], v[50:65]
	s_waitcnt vmcnt(8)
	ds_write_b128 v230, v[66:69]
	s_waitcnt lgkmcnt(2)
	v_mfma_f32_32x32x16_bf16 v[34:49], v[240:243], v[248:251], v[34:49]
	ds_read_b128 v[240:243], v231 offset:18528
	ds_write_b128 v230, v[70:73] offset:36864
	s_waitcnt lgkmcnt(3)
	v_mfma_f32_32x32x16_bf16 v[18:33], v[252:255], v[244:247], v[18:33]
	ds_read_b128 v[244:247], v232 offset:55392
	ds_write_b128 v230, v[74:77] offset:4608
	s_waitcnt lgkmcnt(5)
	v_mfma_f32_32x32x16_bf16 v[2:17], v[252:255], v[248:251], v[2:17]
	ds_read_b128 v[248:251], v232 offset:60000
	ds_read_b128 v[252:255], v231 offset:23136
	ds_write_b128 v230, v[82:85] offset:41472
	s_waitcnt lgkmcnt(4)
	v_mfma_f32_32x32x16_bf16 v[50:65], v[240:243], v[244:247], v[50:65]
	ds_write_b128 v230, v[86:89] offset:9216
	s_waitcnt lgkmcnt(3)
	v_mfma_f32_32x32x16_bf16 v[34:49], v[240:243], v[248:251], v[34:49]
	ds_write_b128 v230, v[94:97] offset:46080
	s_waitcnt lgkmcnt(3)
	v_mfma_f32_32x32x16_bf16 v[18:33], v[252:255], v[244:247], v[18:33]
	ds_write_b128 v230, v[102:105] offset:13824
	s_waitcnt lgkmcnt(4)
	v_mfma_f32_32x32x16_bf16 v[2:17], v[252:255], v[248:251], v[2:17]
	ds_write_b128 v230, v[110:113] offset:50688
	s_setprio 0
	s_add_u32 s34, s34, 0x100
	s_addc_u32 s35, s35, 0
	s_andn2_b64 vcc, exec, s[40:41]
	v_lshl_add_u64 v[218:219], v[218:219], 0, s[24:25]
	s_waitcnt lgkmcnt(0)
	s_barrier
	s_cmp_lt_u32 s44, 12
	s_cbranch_scc1 .Lgf2_top
	s_add_i32 s44, s44, 2
	s_cmp_lt_u32 s44, 14
	s_cselect_b64 s[42:43], -1, 0
	s_cmp_gt_u32 s44, 13
	s_cselect_b64 s[40:41], -1, 0
	s_and_b64 vcc, exec, s[40:41]
	v_lshl_add_u64 v[222:223], s[34:35], 0, v[160:161]
	v_lshl_add_u64 v[220:221], v[218:219], 0, v[158:159]
	s_setprio 1
	ds_read_b128 v[240:243], v231
	ds_read_b128 v[244:247], v232 offset:36864
	ds_read_b128 v[248:251], v232 offset:41472
	ds_read_b128 v[252:255], v231 offset:4608
	s_waitcnt lgkmcnt(2)
	v_mfma_f32_32x32x16_bf16 v[50:65], v[240:243], v[244:247], v[50:65]
	s_waitcnt lgkmcnt(1)
	v_mfma_f32_32x32x16_bf16 v[34:49], v[240:243], v[248:251], v[34:49]
	ds_read_b128 v[240:243], v231 offset:32
	s_waitcnt lgkmcnt(1)
	v_mfma_f32_32x32x16_bf16 v[18:33], v[252:255], v[244:247], v[18:33]
	ds_read_b128 v[244:247], v232 offset:36896
	s_waitcnt lgkmcnt(2)
	v_mfma_f32_32x32x16_bf16 v[2:17], v[252:255], v[248:251], v[2:17]
	ds_read_b128 v[248:251], v232 offset:41504
	ds_read_b128 v[252:255], v231 offset:4640
	s_waitcnt lgkmcnt(2)
	v_mfma_f32_32x32x16_bf16 v[50:65], v[240:243], v[244:247], v[50:65]
	s_waitcnt lgkmcnt(1)
	v_mfma_f32_32x32x16_bf16 v[34:49], v[240:243], v[248:251], v[34:49]
	ds_read_b128 v[240:243], v231 offset:64
	s_waitcnt lgkmcnt(1)
	v_mfma_f32_32x32x16_bf16 v[18:33], v[252:255], v[244:247], v[18:33]
	ds_read_b128 v[244:247], v232 offset:36928
	s_waitcnt lgkmcnt(2)
	v_mfma_f32_32x32x16_bf16 v[2:17], v[252:255], v[248:251], v[2:17]
	ds_read_b128 v[248:251], v232 offset:41536
	ds_read_b128 v[252:255], v231 offset:4672
	s_waitcnt lgkmcnt(2)
	v_mfma_f32_32x32x16_bf16 v[50:65], v[240:243], v[244:247], v[50:65]
	s_waitcnt vmcnt(0)
	ds_write_b128 v230, v[78:81] offset:18432
	s_waitcnt lgkmcnt(2)
	v_mfma_f32_32x32x16_bf16 v[34:49], v[240:243], v[248:251], v[34:49]
	ds_read_b128 v[240:243], v231 offset:96
	ds_write_b128 v230, v[114:117] offset:55296
	s_waitcnt lgkmcnt(3)
	v_mfma_f32_32x32x16_bf16 v[18:33], v[252:255], v[244:247], v[18:33]
	ds_read_b128 v[244:247], v232 offset:36960
	ds_write_b128 v230, v[90:93] offset:23040
	s_waitcnt lgkmcnt(5)
	v_mfma_f32_32x32x16_bf16 v[2:17], v[252:255], v[248:251], v[2:17]
	ds_read_b128 v[248:251], v232 offset:41568
	ds_read_b128 v[252:255], v231 offset:4704
	ds_write_b128 v230, v[118:121] offset:59904
	s_waitcnt lgkmcnt(4)
	v_mfma_f32_32x32x16_bf16 v[50:65], v[240:243], v[244:247], v[50:65]
	ds_write_b128 v230, v[98:101] offset:27648
	s_waitcnt lgkmcnt(3)
	v_mfma_f32_32x32x16_bf16 v[34:49], v[240:243], v[248:251], v[34:49]
	ds_write_b128 v230, v[122:125] offset:64512
	s_waitcnt lgkmcnt(3)
	v_mfma_f32_32x32x16_bf16 v[18:33], v[252:255], v[244:247], v[18:33]
	ds_write_b128 v230, v[106:109] offset:32256
	s_waitcnt lgkmcnt(4)
	v_mfma_f32_32x32x16_bf16 v[2:17], v[252:255], v[248:251], v[2:17]
	ds_write_b128 v233, v[126:129] offset:13824
	s_setprio 0
	s_waitcnt lgkmcnt(0)
	s_barrier
; #define MFMA(a, b, c) __builtin_amdgcn_mfma_f32_32x32x16_bf16((a), (b), (c), 0, 0, 0)
; DI void gemm_mma(const bf16_t* a_, const bf16_t* b_, f32x16 (&acc)[2][2]) {
;   __builtin_amdgcn_s_setprio(1);
; #pragma unroll
;   for (int kk = 0; kk < 4; ++kk) {
;     bf16x8 a0 = *(const bf16x8*)(a_ + kk * 16);
;     bf16x8 a1 = *(const bf16x8*)(a_ + 32 * LDT + kk * 16);
;     bf16x8 b0 = *(const bf16x8*)(b_ + kk * 16);
;     bf16x8 b1 = *(const bf16x8*)(b_ + 32 * LDT + kk * 16);
;     acc[0][0] = MFMA(a0, b0, acc[0][0]);
;     acc[0][1] = MFMA(a0, b1, acc[0][1]);
;     acc[1][0] = MFMA(a1, b0, acc[1][0]);
;     acc[1][1] = MFMA(a1, b1, acc[1][1]);
;   }
;   __builtin_amdgcn_s_setprio(0);
; }
; DI void gemm_tile(const bf16_t* __restrict__ A, int lda, const bf16_t* __restrict__ B, int ldb, int K,
;                   f32x16 (&acc)[2][2], char* smem) {
;     ...
;     gemm_mma(sA + 128 * LDT + aoff, sB + 128 * LDT + boff, acc);
;     if (kt + 2 < nk) gemm_sts(sA, sB, r0, c0, ra0, rb0);
;     __syncthreads();
	s_setprio 1
	ds_read_b128 v[240:243], v231 offset:18432
	ds_read_b128 v[244:247], v232 offset:55296
	ds_read_b128 v[248:251], v232 offset:59904
	ds_read_b128 v[252:255], v231 offset:23040
	s_waitcnt lgkmcnt(2)
	v_mfma_f32_32x32x16_bf16 v[50:65], v[240:243], v[244:247], v[50:65]
	s_waitcnt lgkmcnt(1)
	v_mfma_f32_32x32x16_bf16 v[34:49], v[240:243], v[248:251], v[34:49]
	ds_read_b128 v[240:243], v231 offset:18464
	s_waitcnt lgkmcnt(1)
	v_mfma_f32_32x32x16_bf16 v[18:33], v[252:255], v[244:247], v[18:33]
	ds_read_b128 v[244:247], v232 offset:55328
	s_waitcnt lgkmcnt(2)
	v_mfma_f32_32x32x16_bf16 v[2:17], v[252:255], v[248:251], v[2:17]
	ds_read_b128 v[248:251], v232 offset:59936
	ds_read_b128 v[252:255], v231 offset:23072
	s_waitcnt lgkmcnt(2)
	v_mfma_f32_32x32x16_bf16 v[50:65], v[240:243], v[244:247], v[50:65]
	s_waitcnt lgkmcnt(1)
	v_mfma_f32_32x32x16_bf16 v[34:49], v[240:243], v[248:251], v[34:49]
	ds_read_b128 v[240:243], v231 offset:18496
	s_waitcnt lgkmcnt(1)
	v_mfma_f32_32x32x16_bf16 v[18:33], v[252:255], v[244:247], v[18:33]
	ds_read_b128 v[244:247], v232 offset:55360
	s_waitcnt lgkmcnt(2)
	v_mfma_f32_32x32x16_bf16 v[2:17], v[252:255], v[248:251], v[2:17]
	ds_read_b128 v[248:251], v232 offset:59968
	ds_read_b128 v[252:255], v231 offset:23104
	s_waitcnt lgkmcnt(2)
	v_mfma_f32_32x32x16_bf16 v[50:65], v[240:243], v[244:247], v[50:65]
	s_waitcnt lgkmcnt(1)
	v_mfma_f32_32x32x16_bf16 v[34:49], v[240:243], v[248:251], v[34:49]
	ds_read_b128 v[240:243], v231 offset:18528
	s_waitcnt lgkmcnt(1)
	v_mfma_f32_32x32x16_bf16 v[18:33], v[252:255], v[244:247], v[18:33]
	ds_read_b128 v[244:247], v232 offset:55392
	s_waitcnt lgkmcnt(2)
	v_mfma_f32_32x32x16_bf16 v[2:17], v[252:255], v[248:251], v[2:17]
	ds_read_b128 v[248:251], v232 offset:60000
	ds_read_b128 v[252:255], v231 offset:23136
	s_waitcnt lgkmcnt(2)
	v_mfma_f32_32x32x16_bf16 v[50:65], v[240:243], v[244:247], v[50:65]
	s_waitcnt lgkmcnt(1)
	v_mfma_f32_32x32x16_bf16 v[34:49], v[240:243], v[248:251], v[34:49]
	s_waitcnt lgkmcnt(0)
	v_mfma_f32_32x32x16_bf16 v[18:33], v[252:255], v[244:247], v[18:33]
	s_waitcnt lgkmcnt(0)
	v_mfma_f32_32x32x16_bf16 v[2:17], v[252:255], v[248:251], v[2:17]
	s_setprio 0
	s_add_u32 s34, s34, 0x100
	s_addc_u32 s35, s35, 0
	s_andn2_b64 vcc, exec, s[40:41]
	v_lshl_add_u64 v[218:219], v[218:219], 0, s[24:25]
	s_waitcnt lgkmcnt(0)
	s_barrier
	s_branch .LBB0_294

; DI void gemm_ldg(const bf16_t* ga, const bf16_t* gb, int lda, int ldb, int koff, u32x4 (&ra)[4], u32x4 (&rb)[4]) {
; #pragma unroll
;   for (int i = 0; i < 4; ++i) {
;     ra[i] = *(const u32x4*)(ga + (size_t)(32 * i) * lda + koff);
;     rb[i] = *(const u32x4*)(gb + (size_t)(32 * i) * ldb + koff);
;   }
; }
; DI void gemm_sts(bf16_t* dA, bf16_t* dB, int r0, int c0, const u32x4 (&ra)[4], const u32x4 (&rb)[4]) {
; #pragma unroll
;   for (int i = 0; i < 4; ++i) {
;     *(u32x4*)(dA + (r0 + 32 * i) * LDT + c0 * 8) = ra[i];
;     *(u32x4*)(dB + (r0 + 32 * i) * LDT + c0 * 8) = rb[i];
;   }
; }
; DI void gemm_mma(const bf16_t* a_, const bf16_t* b_, f32x16 (&acc)[2][2]) {
;   __builtin_amdgcn_s_setprio(1);
; #pragma unroll
;   for (int kk = 0; kk < 4; ++kk) {
;     bf16x8 a0 = *(const bf16x8*)(a_ + kk * 16);
;     bf16x8 a1 = *(const bf16x8*)(a_ + 32 * LDT + kk * 16);
;     bf16x8 b0 = *(const bf16x8*)(b_ + kk * 16);
;     bf16x8 b1 = *(const bf16x8*)(b_ + 32 * LDT + kk * 16);
;     acc[0][0] = MFMA(a0, b0, acc[0][0]);
;     acc[0][1] = MFMA(a0, b1, acc[0][1]);
;     acc[1][0] = MFMA(a1, b0, acc[1][0]);
;     acc[1][1] = MFMA(a1, b1, acc[1][1]);
;   }
;   __builtin_amdgcn_s_setprio(0);
; }
; DI void gemm_tile(const bf16_t* __restrict__ A, int lda, const bf16_t* __restrict__ B, int ldb, int K,
;                   f32x16 (&acc)[2][2], char* smem) {
;   const int tid = threadIdx.x, lane = tid & 63, w = tid >> 6, wm = w >> 1, wn = w & 1;
;   bf16_t* sA = (bf16_t*)smem;
;   bf16_t* sB = sA + 2 * 128 * LDT;
;   const int r0 = tid >> 3, c0 = tid & 7;
;   const bf16_t* ga = A + (size_t)r0 * lda + c0 * 8;
;   const bf16_t* gb = B + (size_t)r0 * ldb + c0 * 8;
;   const int aoff = (wm * 64 + (lane & 31)) * LDT + (lane >> 5) * 8;
;   const int boff = (wn * 64 + (lane & 31)) * LDT + (lane >> 5) * 8;
;   u32x4 ra0[4], rb0[4], ra1[4], rb1[4];
;   gemm_ldg(ga, gb, lda, ldb, 0, ra0, rb0);
;   gemm_ldg(ga, gb, lda, ldb, 64, ra1, rb1);
;   __syncthreads();
;   gemm_sts(sA, sB, r0, c0, ra0, rb0);
;   __syncthreads();
;   const int nk = K >> 6;
; #pragma unroll 1
;   for (int kt = 0; kt < nk; kt += 2) {
;     if (kt + 2 < nk) gemm_ldg(ga, gb, lda, ldb, (kt + 2) * 64, ra0, rb0);
;     gemm_mma(sA + aoff, sB + boff, acc);
;     gemm_sts(sA + 128 * LDT, sB + 128 * LDT, r0, c0, ra1, rb1);
;     __syncthreads();
;     if (kt + 3 < nk) gemm_ldg(ga, gb, lda, ldb, (kt + 3) * 64, ra1, rb1);
.Lgf3_top:
	s_add_i32 s10, s10, 2
	s_cmp_lt_u32 s10, 14
	s_cselect_b64 s[20:21], -1, 0
	s_cmp_gt_u32 s10, 13
	s_cselect_b64 s[18:19], -1, 0
	s_and_b64 vcc, exec, s[18:19]
	v_lshl_add_u64 v[152:153], v[148:149], 0, v[144:145]
	v_lshl_add_u64 v[150:151], v[146:147], 0, v[144:145]
	s_setprio 1
	ds_read_b128 v[208:211], v155
	ds_read_b128 v[212:215], v156 offset:36864
	ds_read_b128 v[216:219], v156 offset:41472
	ds_read_b128 v[220:223], v155 offset:4608
	ds_read_b128 v[232:235], v155 offset:32
	ds_read_b128 v[236:239], v156 offset:36896
	ds_read_b128 v[240:243], v156 offset:41504
	ds_read_b128 v[244:247], v155 offset:4640
	s_waitcnt lgkmcnt(6)
	v_mfma_f32_32x32x16_bf16 v[50:65], v[208:211], v[212:215], v[50:65]
	v_add_co_u32_e32 v66, vcc, 0x15300000, v152
	s_nop 1
	v_addc_co_u32_e32 v67, vcc, 0, v153, vcc
	v_add_co_u32_e32 v70, vcc, 0xc00000, v150
	global_load_dwordx4 v[66:69], v[66:67], off offset:256
	s_waitcnt lgkmcnt(5)
	v_mfma_f32_32x32x16_bf16 v[34:49], v[208:211], v[216:219], v[34:49]
	ds_read_b128 v[208:211], v155 offset:64
	s_nop 0
	v_addc_co_u32_e32 v71, vcc, 0, v151, vcc
	v_add_co_u32_e32 v74, vcc, 0x15310000, v152
	global_load_dwordx4 v[70:73], v[70:71], off offset:256
	s_waitcnt lgkmcnt(5)
	v_mfma_f32_32x32x16_bf16 v[18:33], v[220:223], v[212:215], v[18:33]
	ds_read_b128 v[212:215], v156 offset:36928
	s_nop 0
	v_addc_co_u32_e32 v75, vcc, 0, v153, vcc
	v_add_co_u32_e32 v82, vcc, 0xc10000, v150
	global_load_dwordx4 v[74:77], v[74:75], off offset:256
	s_waitcnt lgkmcnt(6)
	v_mfma_f32_32x32x16_bf16 v[2:17], v[220:223], v[216:219], v[2:17]
	ds_read_b128 v[216:219], v156 offset:41536
	ds_read_b128 v[220:223], v155 offset:4672
	s_nop 0
	v_addc_co_u32_e32 v83, vcc, 0, v151, vcc
	v_add_co_u32_e32 v90, vcc, 0x15320000, v152
	global_load_dwordx4 v[82:85], v[82:83], off offset:256
	s_waitcnt lgkmcnt(6)
	v_mfma_f32_32x32x16_bf16 v[50:65], v[232:235], v[236:239], v[50:65]
	s_nop 0
	v_addc_co_u32_e32 v91, vcc, 0, v153, vcc
	v_add_co_u32_e32 v98, vcc, 0xc20000, v150
	global_load_dwordx4 v[90:93], v[90:91], off offset:256
	s_waitcnt lgkmcnt(5)
	v_mfma_f32_32x32x16_bf16 v[34:49], v[232:235], v[240:243], v[34:49]
	ds_read_b128 v[232:235], v155 offset:96
	s_nop 0
	v_addc_co_u32_e32 v99, vcc, 0, v151, vcc
	v_add_co_u32_e32 v110, vcc, 0x15330000, v152
	global_load_dwordx4 v[98:101], v[98:99], off offset:256
	s_waitcnt lgkmcnt(5)
	v_mfma_f32_32x32x16_bf16 v[18:33], v[244:247], v[236:239], v[18:33]
	ds_read_b128 v[236:239], v156 offset:36960
	s_nop 0
	v_addc_co_u32_e32 v111, vcc, 0, v153, vcc
	v_add_co_u32_e32 v126, vcc, s28, v150
	global_load_dwordx4 v[110:113], v[110:111], off offset:256
	s_waitcnt lgkmcnt(6)
	v_mfma_f32_32x32x16_bf16 v[2:17], v[244:247], v[240:243], v[2:17]
	ds_read_b128 v[240:243], v156 offset:41568
	ds_read_b128 v[244:247], v155 offset:4704
	s_nop 0
	v_addc_co_u32_e32 v127, vcc, 0, v151, vcc
	global_load_dwordx4 v[126:129], v[126:127], off offset:256
	s_waitcnt lgkmcnt(6)
	v_mfma_f32_32x32x16_bf16 v[50:65], v[208:211], v[212:215], v[50:65]
	s_waitcnt vmcnt(8)
	ds_write_b128 v154, v[78:81] offset:18432
	s_waitcnt lgkmcnt(6)
	v_mfma_f32_32x32x16_bf16 v[34:49], v[208:211], v[216:219], v[34:49]
	ds_write_b128 v154, v[86:89] offset:55296
	s_waitcnt lgkmcnt(6)
	v_mfma_f32_32x32x16_bf16 v[18:33], v[220:223], v[212:215], v[18:33]
	ds_write_b128 v154, v[94:97] offset:23040
	s_waitcnt lgkmcnt(7)
	v_mfma_f32_32x32x16_bf16 v[2:17], v[220:223], v[216:219], v[2:17]
	ds_write_b128 v154, v[102:105] offset:59904
	s_waitcnt lgkmcnt(6)
	v_mfma_f32_32x32x16_bf16 v[50:65], v[232:235], v[236:239], v[50:65]
	ds_write_b128 v154, v[106:109] offset:27648
	s_waitcnt lgkmcnt(6)
	v_mfma_f32_32x32x16_bf16 v[34:49], v[232:235], v[240:243], v[34:49]
	ds_write_b128 v154, v[118:121] offset:64512
	s_waitcnt lgkmcnt(6)
	v_mfma_f32_32x32x16_bf16 v[18:33], v[244:247], v[236:239], v[18:33]
	ds_write_b128 v154, v[114:117] offset:32256
	s_waitcnt lgkmcnt(7)
	v_mfma_f32_32x32x16_bf16 v[2:17], v[244:247], v[240:243], v[2:17]
	ds_write_b128 v157, v[122:125] offset:13824
	s_setprio 0
	s_waitcnt lgkmcnt(0)
	s_barrier
	s_setprio 1
	ds_read_b128 v[208:211], v155 offset:18432
	ds_read_b128 v[212:215], v156 offset:55296
	ds_read_b128 v[216:219], v156 offset:59904
	ds_read_b128 v[220:223], v155 offset:23040
	ds_read_b128 v[232:235], v155 offset:18464
	ds_read_b128 v[236:239], v156 offset:55328
	ds_read_b128 v[240:243], v156 offset:59936
	ds_read_b128 v[244:247], v155 offset:23072
	s_waitcnt lgkmcnt(6)
	v_mfma_f32_32x32x16_bf16 v[50:65], v[208:211], v[212:215], v[50:65]
	v_add_co_u32_e32 v78, vcc, 0x15300000, v152
	s_nop 1
	v_addc_co_u32_e32 v79, vcc, 0, v153, vcc
	v_add_co_u32_e32 v86, vcc, 0xc00000, v150
	global_load_dwordx4 v[78:81], v[78:79], off offset:384
	s_waitcnt lgkmcnt(5)
	v_mfma_f32_32x32x16_bf16 v[34:49], v[208:211], v[216:219], v[34:49]
	ds_read_b128 v[208:211], v155 offset:18496
	s_nop 0
	v_addc_co_u32_e32 v87, vcc, 0, v151, vcc
	v_add_co_u32_e32 v94, vcc, 0x15310000, v152
	global_load_dwordx4 v[86:89], v[86:87], off offset:384
	s_waitcnt lgkmcnt(5)
	v_mfma_f32_32x32x16_bf16 v[18:33], v[220:223], v[212:215], v[18:33]
	ds_read_b128 v[212:215], v156 offset:55360
	s_nop 0
	v_addc_co_u32_e32 v95, vcc, 0, v153, vcc
	v_add_co_u32_e32 v102, vcc, 0xc10000, v150
	global_load_dwordx4 v[94:97], v[94:95], off offset:384
	s_waitcnt lgkmcnt(6)
	v_mfma_f32_32x32x16_bf16 v[2:17], v[220:223], v[216:219], v[2:17]
	ds_read_b128 v[216:219], v156 offset:59968
	ds_read_b128 v[220:223], v155 offset:23104
	s_nop 0
	v_addc_co_u32_e32 v103, vcc, 0, v151, vcc
	v_add_co_u32_e32 v106, vcc, 0x15320000, v152
	global_load_dwordx4 v[102:105], v[102:103], off offset:384
	s_waitcnt lgkmcnt(6)
; DI void gemm_ldg(const bf16_t* ga, const bf16_t* gb, int lda, int ldb, int koff, u32x4 (&ra)[4], u32x4 (&rb)[4]) {
; #pragma unroll
;   for (int i = 0; i < 4; ++i) {
;     ra[i] = *(const u32x4*)(ga + (size_t)(32 * i) * lda + koff);
;     rb[i] = *(const u32x4*)(gb + (size_t)(32 * i) * ldb + koff);
;   }
; }
; DI void gemm_sts(bf16_t* dA, bf16_t* dB, int r0, int c0, const u32x4 (&ra)[4], const u32x4 (&rb)[4]) {
; #pragma unroll
;   for (int i = 0; i < 4; ++i) {
;     *(u32x4*)(dA + (r0 + 32 * i) * LDT + c0 * 8) = ra[i];
;     *(u32x4*)(dB + (r0 + 32 * i) * LDT + c0 * 8) = rb[i];
;   }
; }
; DI void gemm_mma(const bf16_t* a_, const bf16_t* b_, f32x16 (&acc)[2][2]) {
;   __builtin_amdgcn_s_setprio(1);
; #pragma unroll
;   for (int kk = 0; kk < 4; ++kk) {
;     bf16x8 a0 = *(const bf16x8*)(a_ + kk * 16);
;     bf16x8 a1 = *(const bf16x8*)(a_ + 32 * LDT + kk * 16);
;     bf16x8 b0 = *(const bf16x8*)(b_ + kk * 16);
;     bf16x8 b1 = *(const bf16x8*)(b_ + 32 * LDT + kk * 16);
;     acc[0][0] = MFMA(a0, b0, acc[0][0]);
;     acc[0][1] = MFMA(a0, b1, acc[0][1]);
;     acc[1][0] = MFMA(a1, b0, acc[1][0]);
;     acc[1][1] = MFMA(a1, b1, acc[1][1]);
;   }
;   __builtin_amdgcn_s_setprio(0);
; }
; DI void gemm_tile(const bf16_t* __restrict__ A, int lda, const bf16_t* __restrict__ B, int ldb, int K,
;                   f32x16 (&acc)[2][2], char* smem) {
;   const int tid = threadIdx.x, lane = tid & 63, w = tid >> 6, wm = w >> 1, wn = w & 1;
;   bf16_t* sA = (bf16_t*)smem;
;   bf16_t* sB = sA + 2 * 128 * LDT;
;   const int r0 = tid >> 3, c0 = tid & 7;
;   const bf16_t* ga = A + (size_t)r0 * lda + c0 * 8;
;   const bf16_t* gb = B + (size_t)r0 * ldb + c0 * 8;
;   const int aoff = (wm * 64 + (lane & 31)) * LDT + (lane >> 5) * 8;
;   const int boff = (wn * 64 + (lane & 31)) * LDT + (lane >> 5) * 8;
;   u32x4 ra0[4], rb0[4], ra1[4], rb1[4];
;   gemm_ldg(ga, gb, lda, ldb, 0, ra0, rb0);
;   gemm_ldg(ga, gb, lda, ldb, 64, ra1, rb1);
;   __syncthreads();
;   gemm_sts(sA, sB, r0, c0, ra0, rb0);
;   __syncthreads();
;   const int nk = K >> 6;
; #pragma unroll 1
;   for (int kt = 0; kt < nk; kt += 2) {
;     if (kt + 2 < nk) gemm_ldg(ga, gb, lda, ldb, (kt + 2) * 64, ra0, rb0);
;     gemm_mma(sA + aoff, sB + boff, acc);
;     gemm_sts(sA + 128 * LDT, sB + 128 * LDT, r0, c0, ra1, rb1);
;     __syncthreads();
;     if (kt + 3 < nk) gemm_ldg(ga, gb, lda, ldb, (kt + 3) * 64, ra1, rb1);
	v_mfma_f32_32x32x16_bf16 v[50:65], v[232:235], v[236:239], v[50:65]
	s_nop 0
	v_addc_co_u32_e32 v107, vcc, 0, v153, vcc
	v_add_co_u32_e32 v114, vcc, 0xc20000, v150
	global_load_dwordx4 v[106:109], v[106:107], off offset:384
	s_waitcnt lgkmcnt(5)
	v_mfma_f32_32x32x16_bf16 v[34:49], v[232:235], v[240:243], v[34:49]
	ds_read_b128 v[232:235], v155 offset:18528
	s_nop 0
	v_addc_co_u32_e32 v115, vcc, 0, v151, vcc
	global_load_dwordx4 v[118:121], v[114:115], off offset:384
	s_waitcnt lgkmcnt(5)
	v_mfma_f32_32x32x16_bf16 v[18:33], v[244:247], v[236:239], v[18:33]
	ds_read_b128 v[236:239], v156 offset:55392
	v_add_co_u32_e32 v114, vcc, 0x15330000, v152
	s_nop 1
	v_addc_co_u32_e32 v115, vcc, 0, v153, vcc
	v_add_co_u32_e32 v122, vcc, 0xc30000, v150
	global_load_dwordx4 v[114:117], v[114:115], off offset:384
	s_waitcnt lgkmcnt(6)
	v_mfma_f32_32x32x16_bf16 v[2:17], v[244:247], v[240:243], v[2:17]
	ds_read_b128 v[240:243], v156 offset:60000
	ds_read_b128 v[244:247], v155 offset:23136
	s_nop 0
	v_addc_co_u32_e32 v123, vcc, 0, v151, vcc
	global_load_dwordx4 v[122:125], v[122:123], off offset:384
	s_waitcnt lgkmcnt(6)
	v_mfma_f32_32x32x16_bf16 v[50:65], v[208:211], v[212:215], v[50:65]
	s_waitcnt vmcnt(8)
	ds_write_b128 v154, v[66:69]
	s_waitcnt lgkmcnt(6)
	v_mfma_f32_32x32x16_bf16 v[34:49], v[208:211], v[216:219], v[34:49]
	ds_write_b128 v154, v[70:73] offset:36864
	s_waitcnt lgkmcnt(6)
	v_mfma_f32_32x32x16_bf16 v[18:33], v[220:223], v[212:215], v[18:33]
	ds_write_b128 v154, v[74:77] offset:4608
	s_waitcnt lgkmcnt(7)
	v_mfma_f32_32x32x16_bf16 v[2:17], v[220:223], v[216:219], v[2:17]
	ds_write_b128 v154, v[82:85] offset:41472
	s_waitcnt lgkmcnt(6)
	v_mfma_f32_32x32x16_bf16 v[50:65], v[232:235], v[236:239], v[50:65]
	ds_write_b128 v154, v[90:93] offset:9216
	s_waitcnt lgkmcnt(6)
	v_mfma_f32_32x32x16_bf16 v[34:49], v[232:235], v[240:243], v[34:49]
	ds_write_b128 v154, v[98:101] offset:46080
	s_waitcnt lgkmcnt(6)
	v_mfma_f32_32x32x16_bf16 v[18:33], v[244:247], v[236:239], v[18:33]
	ds_write_b128 v154, v[110:113] offset:13824
	s_waitcnt lgkmcnt(7)
	v_mfma_f32_32x32x16_bf16 v[2:17], v[244:247], v[240:243], v[2:17]
	ds_write_b128 v154, v[126:129] offset:50688
	s_setprio 0
	v_lshl_add_u64 v[146:147], v[146:147], 0, s[16:17]
	s_andn2_b64 vcc, exec, s[18:19]
	v_lshl_add_u64 v[148:149], v[148:149], 0, s[16:17]
	s_waitcnt lgkmcnt(0)
	s_barrier
	s_cmp_lt_u32 s10, 12
	s_cbranch_scc1 .Lgf3_top
; #define MFMA(a, b, c) __builtin_amdgcn_mfma_f32_32x32x16_bf16((a), (b), (c), 0, 0, 0)
; DI void gemm_mma(const bf16_t* a_, const bf16_t* b_, f32x16 (&acc)[2][2]) {
;   __builtin_amdgcn_s_setprio(1);
; #pragma unroll
;   for (int kk = 0; kk < 4; ++kk) {
;     bf16x8 a0 = *(const bf16x8*)(a_ + kk * 16);
;     bf16x8 a1 = *(const bf16x8*)(a_ + 32 * LDT + kk * 16);
;     bf16x8 b0 = *(const bf16x8*)(b_ + kk * 16);
;     bf16x8 b1 = *(const bf16x8*)(b_ + 32 * LDT + kk * 16);
;     acc[0][0] = MFMA(a0, b0, acc[0][0]);
;     acc[0][1] = MFMA(a0, b1, acc[0][1]);
;     acc[1][0] = MFMA(a1, b0, acc[1][0]);
;     acc[1][1] = MFMA(a1, b1, acc[1][1]);
;   }
;   __builtin_amdgcn_s_setprio(0);
; }
; DI void gemm_tile(const bf16_t* __restrict__ A, int lda, const bf16_t* __restrict__ B, int ldb, int K,
;                   f32x16 (&acc)[2][2], char* smem) {
;   const int tid = threadIdx.x, lane = tid & 63, w = tid >> 6, wm = w >> 1, wn = w & 1;
;   bf16_t* sA = (bf16_t*)smem;
;   bf16_t* sB = sA + 2 * 128 * LDT;
;   const int r0 = tid >> 3, c0 = tid & 7;
;   const bf16_t* ga = A + (size_t)r0 * lda + c0 * 8;
;   const bf16_t* gb = B + (size_t)r0 * ldb + c0 * 8;
;   const int aoff = (wm * 64 + (lane & 31)) * LDT + (lane >> 5) * 8;
;   const int boff = (wn * 64 + (lane & 31)) * LDT + (lane >> 5) * 8;
;   u32x4 ra0[4], rb0[4], ra1[4], rb1[4];
;   gemm_ldg(ga, gb, lda, ldb, 0, ra0, rb0);
;   gemm_ldg(ga, gb, lda, ldb, 64, ra1, rb1);
;   __syncthreads();
;   gemm_sts(sA, sB, r0, c0, ra0, rb0);
;   __syncthreads();
;   const int nk = K >> 6;
; #pragma unroll 1
;   for (int kt = 0; kt < nk; kt += 2) {
;     if (kt + 2 < nk) gemm_ldg(ga, gb, lda, ldb, (kt + 2) * 64, ra0, rb0);
;     gemm_mma(sA + aoff, sB + boff, acc);
;     gemm_sts(sA + 128 * LDT, sB + 128 * LDT, r0, c0, ra1, rb1);
;     __syncthreads();
;     if (kt + 3 < nk) gemm_ldg(ga, gb, lda, ldb, (kt + 3) * 64, ra1, rb1);
;     gemm_mma(sA + 128 * LDT + aoff, sB + 128 * LDT + boff, acc);
;     if (kt + 2 < nk) gemm_sts(sA, sB, r0, c0, ra0, rb0);
;     __syncthreads();
;   }
	s_add_i32 s10, s10, 2
	s_cmp_lt_u32 s10, 14
	s_cselect_b64 s[20:21], -1, 0
	s_cmp_gt_u32 s10, 13
	s_cselect_b64 s[18:19], -1, 0
	s_and_b64 vcc, exec, s[18:19]
	v_lshl_add_u64 v[152:153], v[148:149], 0, v[144:145]
	v_lshl_add_u64 v[150:151], v[146:147], 0, v[144:145]
	s_setprio 1
	ds_read_b128 v[208:211], v155
	ds_read_b128 v[212:215], v156 offset:36864
	ds_read_b128 v[216:219], v156 offset:41472
	ds_read_b128 v[220:223], v155 offset:4608
	ds_read_b128 v[232:235], v155 offset:32
	ds_read_b128 v[236:239], v156 offset:36896
	ds_read_b128 v[240:243], v156 offset:41504
	ds_read_b128 v[244:247], v155 offset:4640
	s_waitcnt lgkmcnt(6)
	v_mfma_f32_32x32x16_bf16 v[50:65], v[208:211], v[212:215], v[50:65]
	s_waitcnt lgkmcnt(5)
	v_mfma_f32_32x32x16_bf16 v[34:49], v[208:211], v[216:219], v[34:49]
	ds_read_b128 v[208:211], v155 offset:64
	s_waitcnt lgkmcnt(5)
	v_mfma_f32_32x32x16_bf16 v[18:33], v[220:223], v[212:215], v[18:33]
	ds_read_b128 v[212:215], v156 offset:36928
	s_waitcnt lgkmcnt(6)
	v_mfma_f32_32x32x16_bf16 v[2:17], v[220:223], v[216:219], v[2:17]
	ds_read_b128 v[216:219], v156 offset:41536
	ds_read_b128 v[220:223], v155 offset:4672
	s_waitcnt lgkmcnt(6)
	v_mfma_f32_32x32x16_bf16 v[50:65], v[232:235], v[236:239], v[50:65]
	s_waitcnt lgkmcnt(5)
	v_mfma_f32_32x32x16_bf16 v[34:49], v[232:235], v[240:243], v[34:49]
	ds_read_b128 v[232:235], v155 offset:96
	s_waitcnt lgkmcnt(5)
	v_mfma_f32_32x32x16_bf16 v[18:33], v[244:247], v[236:239], v[18:33]
	ds_read_b128 v[236:239], v156 offset:36960
	s_waitcnt lgkmcnt(6)
	v_mfma_f32_32x32x16_bf16 v[2:17], v[244:247], v[240:243], v[2:17]
	ds_read_b128 v[240:243], v156 offset:41568
	ds_read_b128 v[244:247], v155 offset:4704
	s_waitcnt lgkmcnt(6)
	v_mfma_f32_32x32x16_bf16 v[50:65], v[208:211], v[212:215], v[50:65]
	s_waitcnt vmcnt(0)
	ds_write_b128 v154, v[78:81] offset:18432
	s_waitcnt lgkmcnt(6)
	v_mfma_f32_32x32x16_bf16 v[34:49], v[208:211], v[216:219], v[34:49]
	ds_write_b128 v154, v[86:89] offset:55296
	s_waitcnt lgkmcnt(6)
	v_mfma_f32_32x32x16_bf16 v[18:33], v[220:223], v[212:215], v[18:33]
	ds_write_b128 v154, v[94:97] offset:23040
	s_waitcnt lgkmcnt(7)
	v_mfma_f32_32x32x16_bf16 v[2:17], v[220:223], v[216:219], v[2:17]
	ds_write_b128 v154, v[102:105] offset:59904
	s_waitcnt lgkmcnt(6)
	v_mfma_f32_32x32x16_bf16 v[50:65], v[232:235], v[236:239], v[50:65]
	ds_write_b128 v154, v[106:109] offset:27648
	s_waitcnt lgkmcnt(6)
	v_mfma_f32_32x32x16_bf16 v[34:49], v[232:235], v[240:243], v[34:49]
	ds_write_b128 v154, v[118:121] offset:64512
	s_waitcnt lgkmcnt(6)
	v_mfma_f32_32x32x16_bf16 v[18:33], v[244:247], v[236:239], v[18:33]
	ds_write_b128 v154, v[114:117] offset:32256
	s_waitcnt lgkmcnt(7)
	v_mfma_f32_32x32x16_bf16 v[2:17], v[244:247], v[240:243], v[2:17]
	ds_write_b128 v157, v[122:125] offset:13824
	s_setprio 0
	s_waitcnt lgkmcnt(0)
	s_barrier
	s_setprio 1
	ds_read_b128 v[208:211], v155 offset:18432
	ds_read_b128 v[212:215], v156 offset:55296
	ds_read_b128 v[216:219], v156 offset:59904
	ds_read_b128 v[220:223], v155 offset:23040
	ds_read_b128 v[232:235], v155 offset:18464
	ds_read_b128 v[236:239], v156 offset:55328
	ds_read_b128 v[240:243], v156 offset:59936
	ds_read_b128 v[244:247], v155 offset:23072
	s_waitcnt lgkmcnt(6)
	v_mfma_f32_32x32x16_bf16 v[50:65], v[208:211], v[212:215], v[50:65]
	s_waitcnt lgkmcnt(5)
	v_mfma_f32_32x32x16_bf16 v[34:49], v[208:211], v[216:219], v[34:49]
	ds_read_b128 v[208:211], v155 offset:18496
	s_waitcnt lgkmcnt(5)
	v_mfma_f32_32x32x16_bf16 v[18:33], v[220:223], v[212:215], v[18:33]
	ds_read_b128 v[212:215], v156 offset:55360
	s_waitcnt lgkmcnt(6)
	v_mfma_f32_32x32x16_bf16 v[2:17], v[220:223], v[216:219], v[2:17]
	ds_read_b128 v[216:219], v156 offset:59968
	ds_read_b128 v[220:223], v155 offset:23104
	s_waitcnt lgkmcnt(6)
	v_mfma_f32_32x32x16_bf16 v[50:65], v[232:235], v[236:239], v[50:65]
	s_waitcnt lgkmcnt(5)
	v_mfma_f32_32x32x16_bf16 v[34:49], v[232:235], v[240:243], v[34:49]
	ds_read_b128 v[232:235], v155 offset:18528
	s_waitcnt lgkmcnt(5)
	v_mfma_f32_32x32x16_bf16 v[18:33], v[244:247], v[236:239], v[18:33]
	ds_read_b128 v[236:239], v156 offset:55392
	s_waitcnt lgkmcnt(6)
	v_mfma_f32_32x32x16_bf16 v[2:17], v[244:247], v[240:243], v[2:17]
	ds_read_b128 v[240:243], v156 offset:60000
	ds_read_b128 v[244:247], v155 offset:23136
	s_waitcnt lgkmcnt(6)
	v_mfma_f32_32x32x16_bf16 v[50:65], v[208:211], v[212:215], v[50:65]
	s_waitcnt lgkmcnt(5)
	v_mfma_f32_32x32x16_bf16 v[34:49], v[208:211], v[216:219], v[34:49]
	s_waitcnt lgkmcnt(4)
	v_mfma_f32_32x32x16_bf16 v[18:33], v[220:223], v[212:215], v[18:33]
	s_waitcnt lgkmcnt(4)
	v_mfma_f32_32x32x16_bf16 v[2:17], v[220:223], v[216:219], v[2:17]
	s_waitcnt lgkmcnt(2)
	v_mfma_f32_32x32x16_bf16 v[50:65], v[232:235], v[236:239], v[50:65]
	s_waitcnt lgkmcnt(1)
	v_mfma_f32_32x32x16_bf16 v[34:49], v[232:235], v[240:243], v[34:49]
	s_waitcnt lgkmcnt(0)
	v_mfma_f32_32x32x16_bf16 v[18:33], v[244:247], v[236:239], v[18:33]
	s_waitcnt lgkmcnt(0)
	v_mfma_f32_32x32x16_bf16 v[2:17], v[244:247], v[240:243], v[2:17]
	s_setprio 0
	v_lshl_add_u64 v[146:147], v[146:147], 0, s[16:17]
	s_andn2_b64 vcc, exec, s[18:19]
	v_lshl_add_u64 v[148:149], v[148:149], 0, s[16:17]
	s_waitcnt lgkmcnt(0)
	s_barrier
	s_branch .LBB0_341

; DI void gemm_ldg(const bf16_t* ga, const bf16_t* gb, int lda, int ldb, int koff, u32x4 (&ra)[4], u32x4 (&rb)[4]) {
; #pragma unroll
;   for (int i = 0; i < 4; ++i) {
;     ra[i] = *(const u32x4*)(ga + (size_t)(32 * i) * lda + koff);
;     rb[i] = *(const u32x4*)(gb + (size_t)(32 * i) * ldb + koff);
;   }
; }
; DI void gemm_sts(bf16_t* dA, bf16_t* dB, int r0, int c0, const u32x4 (&ra)[4], const u32x4 (&rb)[4]) {
; #pragma unroll
;   for (int i = 0; i < 4; ++i) {
;     *(u32x4*)(dA + (r0 + 32 * i) * LDT + c0 * 8) = ra[i];
;     *(u32x4*)(dB + (r0 + 32 * i) * LDT + c0 * 8) = rb[i];
;   }
; }
; DI void gemm_mma(const bf16_t* a_, const bf16_t* b_, f32x16 (&acc)[2][2]) {
;   __builtin_amdgcn_s_setprio(1);
; #pragma unroll
;   for (int kk = 0; kk < 4; ++kk) {
;     bf16x8 a0 = *(const bf16x8*)(a_ + kk * 16);
;     bf16x8 a1 = *(const bf16x8*)(a_ + 32 * LDT + kk * 16);
;     bf16x8 b0 = *(const bf16x8*)(b_ + kk * 16);
;     bf16x8 b1 = *(const bf16x8*)(b_ + 32 * LDT + kk * 16);
;     acc[0][0] = MFMA(a0, b0, acc[0][0]);
;     acc[0][1] = MFMA(a0, b1, acc[0][1]);
;     acc[1][0] = MFMA(a1, b0, acc[1][0]);
;     acc[1][1] = MFMA(a1, b1, acc[1][1]);
;   }
;   __builtin_amdgcn_s_setprio(0);
; }
; DI void gemm_tile(const bf16_t* __restrict__ A, int lda, const bf16_t* __restrict__ B, int ldb, int K,
;                   f32x16 (&acc)[2][2], char* smem) {
;   const int tid = threadIdx.x, lane = tid & 63, w = tid >> 6, wm = w >> 1, wn = w & 1;
;   bf16_t* sA = (bf16_t*)smem;
;   bf16_t* sB = sA + 2 * 128 * LDT;
;   const int r0 = tid >> 3, c0 = tid & 7;
;   const bf16_t* ga = A + (size_t)r0 * lda + c0 * 8;
;   const bf16_t* gb = B + (size_t)r0 * ldb + c0 * 8;
;   const int aoff = (wm * 64 + (lane & 31)) * LDT + (lane >> 5) * 8;
;   const int boff = (wn * 64 + (lane & 31)) * LDT + (lane >> 5) * 8;
;   u32x4 ra0[4], rb0[4], ra1[4], rb1[4];
;   gemm_ldg(ga, gb, lda, ldb, 0, ra0, rb0);
;   gemm_ldg(ga, gb, lda, ldb, 64, ra1, rb1);
;   __syncthreads();
;   gemm_sts(sA, sB, r0, c0, ra0, rb0);
;   __syncthreads();
;   const int nk = K >> 6;
; #pragma unroll 1
;   for (int kt = 0; kt < nk; kt += 2) {
;     if (kt + 2 < nk) gemm_ldg(ga, gb, lda, ldb, (kt + 2) * 64, ra0, rb0);
;     gemm_mma(sA + aoff, sB + boff, acc);
;     gemm_sts(sA + 128 * LDT, sB + 128 * LDT, r0, c0, ra1, rb1);
;     __syncthreads();
;     if (kt + 3 < nk) gemm_ldg(ga, gb, lda, ldb, (kt + 3) * 64, ra1, rb1);
.Lgf4_top:
	s_add_i32 s99, s99, 2
	s_cmp_lt_u32 s99, 14
	s_cselect_b64 s[88:89], -1, 0
	s_cmp_gt_u32 s99, 13
	s_cselect_b64 s[86:87], -1, 0
	s_and_b64 vcc, exec, s[86:87]
	v_lshl_add_u64 v[194:195], v[190:191], 0, s[68:69]
	v_lshl_add_u64 v[192:193], v[190:191], 0, s[44:45]
	s_setprio 1
	ds_read_b128 v[232:235], v203
	ds_read_b128 v[236:239], v204 offset:36864
	ds_read_b128 v[240:243], v204 offset:41472
	ds_read_b128 v[244:247], v203 offset:4608
	ds_read_b128 v[248:251], v203 offset:32
	ds_read_b128 v[252:255], v204 offset:36896
	s_waitcnt lgkmcnt(4)
	v_mfma_f32_32x32x16_bf16 v[50:65], v[232:235], v[236:239], v[50:65]
	v_add_co_u32_e32 v66, vcc, 0x5300000, v194
	s_nop 1
	v_addc_co_u32_e32 v67, vcc, 0, v195, vcc
	v_add_co_u32_e32 v70, vcc, 0xe00000, v192
	s_nop 1
	v_addc_co_u32_e32 v71, vcc, 0, v193, vcc
	v_add_co_u32_e32 v78, vcc, 0x5310000, v194
	global_load_dwordx4 v[66:69], v[66:67], off offset:256
	s_waitcnt lgkmcnt(3)
	v_mfma_f32_32x32x16_bf16 v[34:49], v[232:235], v[240:243], v[34:49]
	ds_read_b128 v[232:235], v204 offset:41504
	s_nop 0
	global_load_dwordx4 v[70:73], v[70:71], off offset:256
	s_waitcnt lgkmcnt(3)
	v_mfma_f32_32x32x16_bf16 v[18:33], v[244:247], v[236:239], v[18:33]
	ds_read_b128 v[236:239], v203 offset:4640
	v_addc_co_u32_e32 v79, vcc, 0, v195, vcc
	v_add_co_u32_e32 v82, vcc, 0xe10000, v192
	s_nop 1
	v_addc_co_u32_e32 v83, vcc, 0, v193, vcc
	v_add_co_u32_e32 v90, vcc, 0x5320000, v194
	global_load_dwordx4 v[78:81], v[78:79], off offset:256
	s_waitcnt lgkmcnt(4)
	v_mfma_f32_32x32x16_bf16 v[2:17], v[244:247], v[240:243], v[2:17]
	ds_read_b128 v[240:243], v203 offset:64
	ds_read_b128 v[244:247], v204 offset:36928
	s_nop 0
	global_load_dwordx4 v[82:85], v[82:83], off offset:256
	s_waitcnt lgkmcnt(4)
	v_mfma_f32_32x32x16_bf16 v[50:65], v[248:251], v[252:255], v[50:65]
	v_addc_co_u32_e32 v91, vcc, 0, v195, vcc
	v_add_co_u32_e32 v94, vcc, 0xe20000, v192
	s_nop 1
	v_addc_co_u32_e32 v95, vcc, 0, v193, vcc
	v_add_co_u32_e32 v110, vcc, 0x5330000, v194
	global_load_dwordx4 v[90:93], v[90:91], off offset:256
	s_waitcnt lgkmcnt(3)
	v_mfma_f32_32x32x16_bf16 v[34:49], v[248:251], v[232:235], v[34:49]
	ds_read_b128 v[248:251], v204 offset:41536
	s_nop 0
	global_load_dwordx4 v[94:97], v[94:95], off offset:256
	s_waitcnt lgkmcnt(3)
	v_mfma_f32_32x32x16_bf16 v[18:33], v[236:239], v[252:255], v[18:33]
	ds_read_b128 v[252:255], v203 offset:4672
	v_addc_co_u32_e32 v111, vcc, 0, v195, vcc
	v_add_co_u32_e32 v118, vcc, s90, v192
	s_nop 1
	v_addc_co_u32_e32 v119, vcc, 0, v193, vcc
	global_load_dwordx4 v[110:113], v[110:111], off offset:256
	s_waitcnt lgkmcnt(4)
	v_mfma_f32_32x32x16_bf16 v[2:17], v[236:239], v[232:235], v[2:17]
	ds_read_b128 v[232:235], v203 offset:96
	ds_read_b128 v[236:239], v204 offset:36960
	s_nop 0
	global_load_dwordx4 v[118:121], v[118:119], off offset:256
	s_waitcnt lgkmcnt(4)
	v_mfma_f32_32x32x16_bf16 v[50:65], v[240:243], v[244:247], v[50:65]
	s_waitcnt vmcnt(8)
	ds_write_b128 v202, v[74:77] offset:18432
	s_waitcnt lgkmcnt(4)
	v_mfma_f32_32x32x16_bf16 v[34:49], v[240:243], v[248:251], v[34:49]
	ds_read_b128 v[240:243], v204 offset:41568
	ds_write_b128 v202, v[106:109] offset:55296
	s_waitcnt lgkmcnt(5)
	v_mfma_f32_32x32x16_bf16 v[18:33], v[252:255], v[244:247], v[18:33]
	ds_read_b128 v[244:247], v203 offset:4704
	ds_write_b128 v202, v[86:89] offset:23040
	s_waitcnt lgkmcnt(7)
	v_mfma_f32_32x32x16_bf16 v[2:17], v[252:255], v[248:251], v[2:17]
	ds_write_b128 v202, v[114:117] offset:59904
	s_waitcnt lgkmcnt(6)
	v_mfma_f32_32x32x16_bf16 v[50:65], v[232:235], v[236:239], v[50:65]
	ds_write_b128 v202, v[98:101] offset:27648
	s_waitcnt lgkmcnt(5)
	v_mfma_f32_32x32x16_bf16 v[34:49], v[232:235], v[240:243], v[34:49]
	ds_write_b128 v202, v[122:125] offset:64512
	s_waitcnt lgkmcnt(4)
	v_mfma_f32_32x32x16_bf16 v[18:33], v[244:247], v[236:239], v[18:33]
	ds_write_b128 v202, v[102:105] offset:32256
	s_waitcnt lgkmcnt(5)
	v_mfma_f32_32x32x16_bf16 v[2:17], v[244:247], v[240:243], v[2:17]
	ds_write_b128 v205, v[126:129] offset:13824
	s_setprio 0
	s_waitcnt lgkmcnt(0)
	s_barrier
	s_setprio 1
	ds_read_b128 v[232:235], v203 offset:18432
	ds_read_b128 v[236:239], v204 offset:55296
	ds_read_b128 v[240:243], v204 offset:59904
	ds_read_b128 v[244:247], v203 offset:23040
	ds_read_b128 v[248:251], v203 offset:18464
	ds_read_b128 v[252:255], v204 offset:55328
	s_waitcnt lgkmcnt(4)
	v_mfma_f32_32x32x16_bf16 v[50:65], v[232:235], v[236:239], v[50:65]
	v_add_co_u32_e32 v74, vcc, 0x5300000, v194
	s_nop 1
	v_addc_co_u32_e32 v75, vcc, 0, v195, vcc
	v_add_co_u32_e32 v86, vcc, 0xe00000, v192
	s_nop 1
	v_addc_co_u32_e32 v87, vcc, 0, v193, vcc
	global_load_dwordx4 v[74:77], v[74:75], off offset:384
	s_waitcnt lgkmcnt(3)
	v_mfma_f32_32x32x16_bf16 v[34:49], v[232:235], v[240:243], v[34:49]
	ds_read_b128 v[232:235], v204 offset:59936
	s_nop 0
	global_load_dwordx4 v[106:109], v[86:87], off offset:384
	s_waitcnt lgkmcnt(3)
	v_mfma_f32_32x32x16_bf16 v[18:33], v[244:247], v[236:239], v[18:33]
	ds_read_b128 v[236:239], v203 offset:23072
	v_add_co_u32_e32 v86, vcc, 0x5310000, v194
	s_nop 1
	v_addc_co_u32_e32 v87, vcc, 0, v195, vcc
	v_add_co_u32_e32 v98, vcc, 0xe10000, v192
	s_nop 1
	v_addc_co_u32_e32 v99, vcc, 0, v193, vcc
	global_load_dwordx4 v[86:89], v[86:87], off offset:384
	s_waitcnt lgkmcnt(4)
	v_mfma_f32_32x32x16_bf16 v[2:17], v[244:247], v[240:243], v[2:17]
	ds_read_b128 v[240:243], v203 offset:18496
	ds_read_b128 v[244:247], v204 offset:55360
	s_nop 0
	global_load_dwordx4 v[114:117], v[98:99], off offset:384
	s_waitcnt lgkmcnt(4)
; DI void gemm_ldg(const bf16_t* ga, const bf16_t* gb, int lda, int ldb, int koff, u32x4 (&ra)[4], u32x4 (&rb)[4]) {
; #pragma unroll
;   for (int i = 0; i < 4; ++i) {
;     ra[i] = *(const u32x4*)(ga + (size_t)(32 * i) * lda + koff);
;     rb[i] = *(const u32x4*)(gb + (size_t)(32 * i) * ldb + koff);
;   }
; }
; DI void gemm_sts(bf16_t* dA, bf16_t* dB, int r0, int c0, const u32x4 (&ra)[4], const u32x4 (&rb)[4]) {
; #pragma unroll
;   for (int i = 0; i < 4; ++i) {
;     *(u32x4*)(dA + (r0 + 32 * i) * LDT + c0 * 8) = ra[i];
;     *(u32x4*)(dB + (r0 + 32 * i) * LDT + c0 * 8) = rb[i];
;   }
; }
; DI void gemm_mma(const bf16_t* a_, const bf16_t* b_, f32x16 (&acc)[2][2]) {
;   __builtin_amdgcn_s_setprio(1);
; #pragma unroll
;   for (int kk = 0; kk < 4; ++kk) {
;     bf16x8 a0 = *(const bf16x8*)(a_ + kk * 16);
;     bf16x8 a1 = *(const bf16x8*)(a_ + 32 * LDT + kk * 16);
;     bf16x8 b0 = *(const bf16x8*)(b_ + kk * 16);
;     bf16x8 b1 = *(const bf16x8*)(b_ + 32 * LDT + kk * 16);
;     acc[0][0] = MFMA(a0, b0, acc[0][0]);
;     acc[0][1] = MFMA(a0, b1, acc[0][1]);
;     acc[1][0] = MFMA(a1, b0, acc[1][0]);
;     acc[1][1] = MFMA(a1, b1, acc[1][1]);
;   }
;   __builtin_amdgcn_s_setprio(0);
; }
; DI void gemm_tile(const bf16_t* __restrict__ A, int lda, const bf16_t* __restrict__ B, int ldb, int K,
;                   f32x16 (&acc)[2][2], char* smem) {
;   const int tid = threadIdx.x, lane = tid & 63, w = tid >> 6, wm = w >> 1, wn = w & 1;
;   bf16_t* sA = (bf16_t*)smem;
;   bf16_t* sB = sA + 2 * 128 * LDT;
;   const int r0 = tid >> 3, c0 = tid & 7;
;   const bf16_t* ga = A + (size_t)r0 * lda + c0 * 8;
;   const bf16_t* gb = B + (size_t)r0 * ldb + c0 * 8;
;   const int aoff = (wm * 64 + (lane & 31)) * LDT + (lane >> 5) * 8;
;   const int boff = (wn * 64 + (lane & 31)) * LDT + (lane >> 5) * 8;
;   u32x4 ra0[4], rb0[4], ra1[4], rb1[4];
;   gemm_ldg(ga, gb, lda, ldb, 0, ra0, rb0);
;   gemm_ldg(ga, gb, lda, ldb, 64, ra1, rb1);
;   __syncthreads();
;   gemm_sts(sA, sB, r0, c0, ra0, rb0);
;   __syncthreads();
;   const int nk = K >> 6;
; #pragma unroll 1
;   for (int kt = 0; kt < nk; kt += 2) {
;     if (kt + 2 < nk) gemm_ldg(ga, gb, lda, ldb, (kt + 2) * 64, ra0, rb0);
;     gemm_mma(sA + aoff, sB + boff, acc);
;     gemm_sts(sA + 128 * LDT, sB + 128 * LDT, r0, c0, ra1, rb1);
;     __syncthreads();
;     if (kt + 3 < nk) gemm_ldg(ga, gb, lda, ldb, (kt + 3) * 64, ra1, rb1);
	v_mfma_f32_32x32x16_bf16 v[50:65], v[248:251], v[252:255], v[50:65]
	v_add_co_u32_e32 v98, vcc, 0x5320000, v194
	s_nop 1
	v_addc_co_u32_e32 v99, vcc, 0, v195, vcc
	v_add_co_u32_e32 v102, vcc, 0xe20000, v192
	s_nop 1
	v_addc_co_u32_e32 v103, vcc, 0, v193, vcc
	global_load_dwordx4 v[98:101], v[98:99], off offset:384
	s_waitcnt lgkmcnt(3)
	v_mfma_f32_32x32x16_bf16 v[34:49], v[248:251], v[232:235], v[34:49]
	ds_read_b128 v[248:251], v204 offset:59968
	s_nop 0
	global_load_dwordx4 v[122:125], v[102:103], off offset:384
	s_waitcnt lgkmcnt(3)
	v_mfma_f32_32x32x16_bf16 v[18:33], v[236:239], v[252:255], v[18:33]
	ds_read_b128 v[252:255], v203 offset:23104
	v_add_co_u32_e32 v102, vcc, 0x5330000, v194
	s_nop 1
	v_addc_co_u32_e32 v103, vcc, 0, v195, vcc
	v_add_co_u32_e32 v126, vcc, 0xe30000, v192
	s_nop 1
	v_addc_co_u32_e32 v127, vcc, 0, v193, vcc
	global_load_dwordx4 v[102:105], v[102:103], off offset:384
	s_waitcnt lgkmcnt(4)
	v_mfma_f32_32x32x16_bf16 v[2:17], v[236:239], v[232:235], v[2:17]
	ds_read_b128 v[232:235], v203 offset:18528
	ds_read_b128 v[236:239], v204 offset:55392
	s_nop 0
	global_load_dwordx4 v[126:129], v[126:127], off offset:384
	s_waitcnt lgkmcnt(4)
	v_mfma_f32_32x32x16_bf16 v[50:65], v[240:243], v[244:247], v[50:65]
	s_waitcnt vmcnt(8)
	ds_write_b128 v202, v[66:69]
	s_waitcnt lgkmcnt(4)
	v_mfma_f32_32x32x16_bf16 v[34:49], v[240:243], v[248:251], v[34:49]
	ds_read_b128 v[240:243], v204 offset:60000
	ds_write_b128 v202, v[70:73] offset:36864
	s_waitcnt lgkmcnt(5)
	v_mfma_f32_32x32x16_bf16 v[18:33], v[252:255], v[244:247], v[18:33]
	ds_read_b128 v[244:247], v203 offset:23136
	ds_write_b128 v202, v[78:81] offset:4608
	s_waitcnt lgkmcnt(7)
	v_mfma_f32_32x32x16_bf16 v[2:17], v[252:255], v[248:251], v[2:17]
	ds_write_b128 v202, v[82:85] offset:41472
	s_waitcnt lgkmcnt(6)
	v_mfma_f32_32x32x16_bf16 v[50:65], v[232:235], v[236:239], v[50:65]
	ds_write_b128 v202, v[90:93] offset:9216
	s_waitcnt lgkmcnt(5)
	v_mfma_f32_32x32x16_bf16 v[34:49], v[232:235], v[240:243], v[34:49]
	ds_write_b128 v202, v[94:97] offset:46080
	s_waitcnt lgkmcnt(4)
	v_mfma_f32_32x32x16_bf16 v[18:33], v[244:247], v[236:239], v[18:33]
	ds_write_b128 v202, v[110:113] offset:13824
	s_waitcnt lgkmcnt(5)
	v_mfma_f32_32x32x16_bf16 v[2:17], v[244:247], v[240:243], v[2:17]
	ds_write_b128 v202, v[118:121] offset:50688
	s_setprio 0
	s_andn2_b64 vcc, exec, s[86:87]
	v_lshl_add_u64 v[190:191], v[190:191], 0, s[64:65]
	s_waitcnt lgkmcnt(0)
	s_barrier
	s_cmp_lt_u32 s99, 12
	s_cbranch_scc1 .Lgf4_top
; #define MFMA(a, b, c) __builtin_amdgcn_mfma_f32_32x32x16_bf16((a), (b), (c), 0, 0, 0)
; DI void gemm_mma(const bf16_t* a_, const bf16_t* b_, f32x16 (&acc)[2][2]) {
;   __builtin_amdgcn_s_setprio(1);
; #pragma unroll
;   for (int kk = 0; kk < 4; ++kk) {
;     bf16x8 a0 = *(const bf16x8*)(a_ + kk * 16);
;     bf16x8 a1 = *(const bf16x8*)(a_ + 32 * LDT + kk * 16);
;     bf16x8 b0 = *(const bf16x8*)(b_ + kk * 16);
;     bf16x8 b1 = *(const bf16x8*)(b_ + 32 * LDT + kk * 16);
;     acc[0][0] = MFMA(a0, b0, acc[0][0]);
;     acc[0][1] = MFMA(a0, b1, acc[0][1]);
;     acc[1][0] = MFMA(a1, b0, acc[1][0]);
;     acc[1][1] = MFMA(a1, b1, acc[1][1]);
;   }
;   __builtin_amdgcn_s_setprio(0);
; }
; DI void gemm_tile(const bf16_t* __restrict__ A, int lda, const bf16_t* __restrict__ B, int ldb, int K,
;                   f32x16 (&acc)[2][2], char* smem) {
;   const int tid = threadIdx.x, lane = tid & 63, w = tid >> 6, wm = w >> 1, wn = w & 1;
;   bf16_t* sA = (bf16_t*)smem;
;   bf16_t* sB = sA + 2 * 128 * LDT;
;   const int r0 = tid >> 3, c0 = tid & 7;
;   const bf16_t* ga = A + (size_t)r0 * lda + c0 * 8;
;   const bf16_t* gb = B + (size_t)r0 * ldb + c0 * 8;
;   const int aoff = (wm * 64 + (lane & 31)) * LDT + (lane >> 5) * 8;
;   const int boff = (wn * 64 + (lane & 31)) * LDT + (lane >> 5) * 8;
;   u32x4 ra0[4], rb0[4], ra1[4], rb1[4];
;   gemm_ldg(ga, gb, lda, ldb, 0, ra0, rb0);
;   gemm_ldg(ga, gb, lda, ldb, 64, ra1, rb1);
;   __syncthreads();
;   gemm_sts(sA, sB, r0, c0, ra0, rb0);
;   __syncthreads();
;   const int nk = K >> 6;
; #pragma unroll 1
;   for (int kt = 0; kt < nk; kt += 2) {
;     if (kt + 2 < nk) gemm_ldg(ga, gb, lda, ldb, (kt + 2) * 64, ra0, rb0);
;     gemm_mma(sA + aoff, sB + boff, acc);
;     gemm_sts(sA + 128 * LDT, sB + 128 * LDT, r0, c0, ra1, rb1);
;     __syncthreads();
;     if (kt + 3 < nk) gemm_ldg(ga, gb, lda, ldb, (kt + 3) * 64, ra1, rb1);
;     gemm_mma(sA + 128 * LDT + aoff, sB + 128 * LDT + boff, acc);
;     if (kt + 2 < nk) gemm_sts(sA, sB, r0, c0, ra0, rb0);
;     __syncthreads();
;   }
	s_add_i32 s99, s99, 2
	s_cmp_lt_u32 s99, 14
	s_cselect_b64 s[88:89], -1, 0
	s_cmp_gt_u32 s99, 13
	s_cselect_b64 s[86:87], -1, 0
	s_and_b64 vcc, exec, s[86:87]
	v_lshl_add_u64 v[194:195], v[190:191], 0, s[68:69]
	v_lshl_add_u64 v[192:193], v[190:191], 0, s[44:45]
	s_setprio 1
	ds_read_b128 v[232:235], v203
	ds_read_b128 v[236:239], v204 offset:36864
	ds_read_b128 v[240:243], v204 offset:41472
	ds_read_b128 v[244:247], v203 offset:4608
	ds_read_b128 v[248:251], v203 offset:32
	ds_read_b128 v[252:255], v204 offset:36896
	s_waitcnt lgkmcnt(4)
	v_mfma_f32_32x32x16_bf16 v[50:65], v[232:235], v[236:239], v[50:65]
	s_waitcnt lgkmcnt(3)
	v_mfma_f32_32x32x16_bf16 v[34:49], v[232:235], v[240:243], v[34:49]
	ds_read_b128 v[232:235], v204 offset:41504
	s_waitcnt lgkmcnt(3)
	v_mfma_f32_32x32x16_bf16 v[18:33], v[244:247], v[236:239], v[18:33]
	ds_read_b128 v[236:239], v203 offset:4640
	s_waitcnt lgkmcnt(4)
	v_mfma_f32_32x32x16_bf16 v[2:17], v[244:247], v[240:243], v[2:17]
	ds_read_b128 v[240:243], v203 offset:64
	ds_read_b128 v[244:247], v204 offset:36928
	s_waitcnt lgkmcnt(4)
	v_mfma_f32_32x32x16_bf16 v[50:65], v[248:251], v[252:255], v[50:65]
	s_waitcnt lgkmcnt(3)
	v_mfma_f32_32x32x16_bf16 v[34:49], v[248:251], v[232:235], v[34:49]
	ds_read_b128 v[248:251], v204 offset:41536
	s_waitcnt lgkmcnt(3)
	v_mfma_f32_32x32x16_bf16 v[18:33], v[236:239], v[252:255], v[18:33]
	ds_read_b128 v[252:255], v203 offset:4672
	s_waitcnt lgkmcnt(4)
	v_mfma_f32_32x32x16_bf16 v[2:17], v[236:239], v[232:235], v[2:17]
	ds_read_b128 v[232:235], v203 offset:96
	ds_read_b128 v[236:239], v204 offset:36960
	s_waitcnt lgkmcnt(4)
	v_mfma_f32_32x32x16_bf16 v[50:65], v[240:243], v[244:247], v[50:65]
	s_waitcnt vmcnt(0)
	ds_write_b128 v202, v[74:77] offset:18432
	s_waitcnt lgkmcnt(4)
	v_mfma_f32_32x32x16_bf16 v[34:49], v[240:243], v[248:251], v[34:49]
	ds_read_b128 v[240:243], v204 offset:41568
	ds_write_b128 v202, v[106:109] offset:55296
	s_waitcnt lgkmcnt(5)
	v_mfma_f32_32x32x16_bf16 v[18:33], v[252:255], v[244:247], v[18:33]
	ds_read_b128 v[244:247], v203 offset:4704
	ds_write_b128 v202, v[86:89] offset:23040
	s_waitcnt lgkmcnt(7)
	v_mfma_f32_32x32x16_bf16 v[2:17], v[252:255], v[248:251], v[2:17]
	ds_write_b128 v202, v[114:117] offset:59904
	s_waitcnt lgkmcnt(6)
	v_mfma_f32_32x32x16_bf16 v[50:65], v[232:235], v[236:239], v[50:65]
	ds_write_b128 v202, v[98:101] offset:27648
	s_waitcnt lgkmcnt(5)
	v_mfma_f32_32x32x16_bf16 v[34:49], v[232:235], v[240:243], v[34:49]
	ds_write_b128 v202, v[122:125] offset:64512
	s_waitcnt lgkmcnt(4)
	v_mfma_f32_32x32x16_bf16 v[18:33], v[244:247], v[236:239], v[18:33]
	ds_write_b128 v202, v[102:105] offset:32256
	s_waitcnt lgkmcnt(5)
	v_mfma_f32_32x32x16_bf16 v[2:17], v[244:247], v[240:243], v[2:17]
	ds_write_b128 v205, v[126:129] offset:13824
	s_setprio 0
	s_waitcnt lgkmcnt(0)
	s_barrier
	s_setprio 1
	ds_read_b128 v[232:235], v203 offset:18432
	ds_read_b128 v[236:239], v204 offset:55296
	ds_read_b128 v[240:243], v204 offset:59904
	ds_read_b128 v[244:247], v203 offset:23040
	ds_read_b128 v[248:251], v203 offset:18464
	ds_read_b128 v[252:255], v204 offset:55328
	s_waitcnt lgkmcnt(4)
	v_mfma_f32_32x32x16_bf16 v[50:65], v[232:235], v[236:239], v[50:65]
	s_waitcnt lgkmcnt(3)
	v_mfma_f32_32x32x16_bf16 v[34:49], v[232:235], v[240:243], v[34:49]
	ds_read_b128 v[232:235], v204 offset:59936
	s_waitcnt lgkmcnt(3)
	v_mfma_f32_32x32x16_bf16 v[18:33], v[244:247], v[236:239], v[18:33]
	ds_read_b128 v[236:239], v203 offset:23072
	s_waitcnt lgkmcnt(4)
	v_mfma_f32_32x32x16_bf16 v[2:17], v[244:247], v[240:243], v[2:17]
	ds_read_b128 v[240:243], v203 offset:18496
	ds_read_b128 v[244:247], v204 offset:55360
	s_waitcnt lgkmcnt(4)
	v_mfma_f32_32x32x16_bf16 v[50:65], v[248:251], v[252:255], v[50:65]
	s_waitcnt lgkmcnt(3)
	v_mfma_f32_32x32x16_bf16 v[34:49], v[248:251], v[232:235], v[34:49]
	ds_read_b128 v[248:251], v204 offset:59968
	s_waitcnt lgkmcnt(3)
	v_mfma_f32_32x32x16_bf16 v[18:33], v[236:239], v[252:255], v[18:33]
	ds_read_b128 v[252:255], v203 offset:23104
	s_waitcnt lgkmcnt(4)
	v_mfma_f32_32x32x16_bf16 v[2:17], v[236:239], v[232:235], v[2:17]
	ds_read_b128 v[232:235], v203 offset:18528
	ds_read_b128 v[236:239], v204 offset:55392
	s_waitcnt lgkmcnt(4)
	v_mfma_f32_32x32x16_bf16 v[50:65], v[240:243], v[244:247], v[50:65]
	s_waitcnt lgkmcnt(3)
	v_mfma_f32_32x32x16_bf16 v[34:49], v[240:243], v[248:251], v[34:49]
	ds_read_b128 v[240:243], v204 offset:60000
	s_waitcnt lgkmcnt(3)
	v_mfma_f32_32x32x16_bf16 v[18:33], v[252:255], v[244:247], v[18:33]
	ds_read_b128 v[244:247], v203 offset:23136
	s_waitcnt lgkmcnt(4)
	v_mfma_f32_32x32x16_bf16 v[2:17], v[252:255], v[248:251], v[2:17]
	s_waitcnt lgkmcnt(2)
	v_mfma_f32_32x32x16_bf16 v[50:65], v[232:235], v[236:239], v[50:65]
	s_waitcnt lgkmcnt(1)
	v_mfma_f32_32x32x16_bf16 v[34:49], v[232:235], v[240:243], v[34:49]
	s_waitcnt lgkmcnt(0)
	v_mfma_f32_32x32x16_bf16 v[18:33], v[244:247], v[236:239], v[18:33]
	s_waitcnt lgkmcnt(0)
	v_mfma_f32_32x32x16_bf16 v[2:17], v[244:247], v[240:243], v[2:17]
	s_setprio 0
	s_andn2_b64 vcc, exec, s[86:87]
	v_lshl_add_u64 v[190:191], v[190:191], 0, s[64:65]
	s_waitcnt lgkmcnt(0)
	s_barrier
	s_branch .LBB0_468
